# RG-LRU tile loops: gate bias folded into the MFMA accumulator init (srcC) instead of 64 v_add per tile, max(1-a*a,0) via the v_fma clamp bit instead of 32 v_max
# baseline (speedup 1.0000x reference)
.LBB0_1521:
	v_mov_b32_e32 v212, v126
	v_mov_b32_e32 v213, v126
	v_mov_b32_e32 v214, v126
	v_mov_b32_e32 v215, v126
	v_mov_b32_e32 v216, v127
	v_mov_b32_e32 v217, v127
	v_mov_b32_e32 v218, v127
	v_mov_b32_e32 v219, v127
	v_mov_b32_e32 v220, v128
	v_mov_b32_e32 v221, v128
	v_mov_b32_e32 v222, v128
	v_mov_b32_e32 v223, v128
	v_mov_b32_e32 v224, v129
	v_mov_b32_e32 v225, v129
	v_mov_b32_e32 v226, v129
	v_mov_b32_e32 v227, v129
	s_lshl_b32 s99, s6, 6
	s_add_i32 s11, s6, s73
	v_and_b32_e32 v98, 31, v154
	v_lshrrev_b32_e32 v99, 5, v154
	v_lshlrev_b32_e32 v136, 4, v98
	v_add_u32_e32 v136, 0xf0, v136
	v_lshlrev_b32_e32 v141, 3, v98
	v_add_u32_e32 v141, 0xf0, v141
	v_lshl_add_u32 v137, v99, 2, s99
	v_mov_b32_e32 v140, 0x110
	v_mad_u32_u24 v137, v137, v140, v141
	ds_read_b128 v[64:67], v136
	ds_read_b128 v[80:83], v136 offset:2048
	ds_read_b64 v[84:85], v137 offset:55296
	ds_read_b128 v[68:71], v136 offset:512
	ds_read_b64 v[86:87], v137 offset:55568
	ds_read_b128 v[72:75], v136 offset:1024
	ds_read_b64 v[88:89], v137 offset:55840
	ds_read_b128 v[76:79], v136 offset:1536
	ds_read_b64 v[90:91], v137 offset:56112
	ds_read_b64 v[92:93], v137 offset:56384
	ds_read_b64 v[94:95], v137 offset:56656
	ds_read_b64 v[96:97], v137 offset:56928
	v_and_b32_e32 v138, 3, v99
	v_lshlrev_b32_e32 v138, 4, v138
	v_lshrrev_b32_e32 v139, 2, v99
	v_lshl_add_u32 v98, v139, 2, v138
	v_mad_u32_u24 v139, v98, v140, v141
	v_mov_b32_e32 v140, 0x210
	v_mad_u32_u24 v138, v98, v140, v136
	s_waitcnt lgkmcnt(10)
	v_mov_b64_e32 v[100:101], v[80:81]
	v_mov_b64_e32 v[102:103], v[82:83]
	v_mov_b64_e32 v[104:105], v[80:81]
	v_mov_b64_e32 v[106:107], v[82:83]
	v_mov_b64_e32 v[108:109], v[80:81]
	v_mov_b64_e32 v[110:111], v[82:83]
	v_mov_b64_e32 v[112:113], v[80:81]
	v_mov_b64_e32 v[114:115], v[82:83]
	s_waitcnt lgkmcnt(9)
	v_lshlrev_b32_e32 v132, 16, v84
	v_and_b32_e32 v133, 0xffff0000, v84
	v_lshlrev_b32_e32 v134, 16, v85
	v_and_b32_e32 v135, 0xffff0000, v85
	v_fmac_f32_e32 v100, v132, v64
	v_fmac_f32_e32 v101, v133, v65
	v_fmac_f32_e32 v102, v134, v66
	v_fmac_f32_e32 v103, v135, v67
	s_waitcnt lgkmcnt(7)
	v_lshlrev_b32_e32 v132, 16, v86
	v_and_b32_e32 v133, 0xffff0000, v86
	v_lshlrev_b32_e32 v134, 16, v87
	v_and_b32_e32 v135, 0xffff0000, v87
	v_fmac_f32_e32 v104, v132, v64
	v_fmac_f32_e32 v105, v133, v65
	v_fmac_f32_e32 v106, v134, v66
	v_fmac_f32_e32 v107, v135, v67
	v_fmac_f32_e32 v100, v132, v68
	v_fmac_f32_e32 v101, v133, v69
	v_fmac_f32_e32 v102, v134, v70
	v_fmac_f32_e32 v103, v135, v71
	s_waitcnt lgkmcnt(5)
	v_lshlrev_b32_e32 v132, 16, v88
	v_and_b32_e32 v133, 0xffff0000, v88
	v_lshlrev_b32_e32 v134, 16, v89
	v_and_b32_e32 v135, 0xffff0000, v89
	v_fmac_f32_e32 v108, v132, v64
	v_fmac_f32_e32 v109, v133, v65
	v_fmac_f32_e32 v110, v134, v66
	v_fmac_f32_e32 v111, v135, v67
	v_fmac_f32_e32 v104, v132, v68
	v_fmac_f32_e32 v105, v133, v69
	v_fmac_f32_e32 v106, v134, v70
	v_fmac_f32_e32 v107, v135, v71
	v_fmac_f32_e32 v100, v132, v72
	v_fmac_f32_e32 v101, v133, v73
	v_fmac_f32_e32 v102, v134, v74
	v_fmac_f32_e32 v103, v135, v75
	s_waitcnt lgkmcnt(3)
	v_lshlrev_b32_e32 v132, 16, v90
	v_and_b32_e32 v133, 0xffff0000, v90
	v_lshlrev_b32_e32 v134, 16, v91
	v_and_b32_e32 v135, 0xffff0000, v91
	v_fmac_f32_e32 v112, v132, v64
	v_fmac_f32_e32 v113, v133, v65
	v_fmac_f32_e32 v114, v134, v66
	v_fmac_f32_e32 v115, v135, v67
	v_fmac_f32_e32 v108, v132, v68
	v_fmac_f32_e32 v109, v133, v69
	v_fmac_f32_e32 v110, v134, v70
	v_fmac_f32_e32 v111, v135, v71
	v_fmac_f32_e32 v104, v132, v72
	v_fmac_f32_e32 v105, v133, v73
	v_fmac_f32_e32 v106, v134, v74
	v_fmac_f32_e32 v107, v135, v75
	v_fmac_f32_e32 v100, v132, v76
	v_fmac_f32_e32 v101, v133, v77
	v_fmac_f32_e32 v102, v134, v78
	v_fmac_f32_e32 v103, v135, v79
	s_waitcnt lgkmcnt(2)
	v_lshlrev_b32_e32 v132, 16, v92
	v_and_b32_e32 v133, 0xffff0000, v92
	v_lshlrev_b32_e32 v134, 16, v93
	v_and_b32_e32 v135, 0xffff0000, v93
	v_fmac_f32_e32 v112, v132, v68
	v_fmac_f32_e32 v113, v133, v69
	v_fmac_f32_e32 v114, v134, v70
	v_fmac_f32_e32 v115, v135, v71
	v_fmac_f32_e32 v108, v132, v72
	v_fmac_f32_e32 v109, v133, v73
	v_fmac_f32_e32 v110, v134, v74
	v_fmac_f32_e32 v111, v135, v75
	v_fmac_f32_e32 v104, v132, v76
	v_fmac_f32_e32 v105, v133, v77
	v_fmac_f32_e32 v106, v134, v78
	v_fmac_f32_e32 v107, v135, v79
	s_waitcnt lgkmcnt(1)
	v_lshlrev_b32_e32 v132, 16, v94
	v_and_b32_e32 v133, 0xffff0000, v94
	v_lshlrev_b32_e32 v134, 16, v95
	v_and_b32_e32 v135, 0xffff0000, v95
	v_fmac_f32_e32 v112, v132, v72
	v_fmac_f32_e32 v113, v133, v73
	v_fmac_f32_e32 v114, v134, v74
	v_fmac_f32_e32 v115, v135, v75
	v_fmac_f32_e32 v108, v132, v76
	v_fmac_f32_e32 v109, v133, v77
	v_fmac_f32_e32 v110, v134, v78
	v_fmac_f32_e32 v111, v135, v79
	s_waitcnt lgkmcnt(0)
	v_lshlrev_b32_e32 v132, 16, v96
	v_and_b32_e32 v133, 0xffff0000, v96
	v_lshlrev_b32_e32 v134, 16, v97
	v_and_b32_e32 v135, 0xffff0000, v97
	v_fmac_f32_e32 v112, v132, v76
	v_fmac_f32_e32 v113, v133, v77
	v_fmac_f32_e32 v114, v134, v78
	v_fmac_f32_e32 v115, v135, v79
	ds_write_b128 v138, v[100:103] offset:4096
	ds_write_b128 v138, v[104:107] offset:4624
	ds_write_b128 v138, v[108:111] offset:5152
	ds_write_b128 v138, v[112:115] offset:5680
	v_cvt_pk_bf16_f32 v84, v100, v101
	v_cvt_pk_bf16_f32 v85, v102, v103
	v_cvt_pk_bf16_f32 v86, v104, v105
	v_cvt_pk_bf16_f32 v87, v106, v107
	v_cvt_pk_bf16_f32 v88, v108, v109
	v_cvt_pk_bf16_f32 v89, v110, v111
	v_cvt_pk_bf16_f32 v90, v112, v113
	v_cvt_pk_bf16_f32 v91, v114, v115
	ds_write_b64 v139, v[84:85] offset:37888
	ds_write_b64 v139, v[86:87] offset:38160
	ds_write_b64 v139, v[88:89] offset:38432
	ds_write_b64 v139, v[90:91] offset:38704
	s_waitcnt lgkmcnt(0)
	s_barrier
	ds_read_b128 v[64:67], v159 offset:37888
	ds_read_b128 v[68:71], v159 offset:37952
	ds_read_b128 v[84:87], v159 offset:42240
	ds_read_b128 v[88:91], v159 offset:42304
	ds_read_b128 v[104:107], v159 offset:46592
	ds_read_b128 v[108:111], v159 offset:46656
	ds_read_b128 v[140:143], v159 offset:50944
	ds_read_b128 v[144:147], v159 offset:51008
	s_waitcnt lgkmcnt(7)
	v_mfma_f32_16x16x32_bf16 v[72:75], v[64:67], v[0:3], v[216:219]
	v_mfma_f32_16x16x32_bf16 v[76:79], v[64:67], v[20:23], v[224:227]
	v_mfma_f32_16x16x32_bf16 v[80:83], v[64:67], v[36:39], v[212:215]
	v_mfma_f32_16x16x32_bf16 v[64:67], v[64:67], v[56:59], v[220:223]
	s_waitcnt lgkmcnt(5)
	v_mfma_f32_16x16x32_bf16 v[92:95], v[84:87], v[0:3], v[216:219]
	v_mfma_f32_16x16x32_bf16 v[96:99], v[84:87], v[20:23], v[224:227]
	v_mfma_f32_16x16x32_bf16 v[100:103], v[84:87], v[36:39], v[212:215]
	v_mfma_f32_16x16x32_bf16 v[84:87], v[84:87], v[56:59], v[220:223]
	s_waitcnt lgkmcnt(3)
	v_mfma_f32_16x16x32_bf16 v[112:115], v[104:107], v[0:3], v[216:219]
	v_mfma_f32_16x16x32_bf16 v[132:135], v[104:107], v[20:23], v[224:227]
	v_mfma_f32_16x16x32_bf16 v[136:139], v[104:107], v[36:39], v[212:215]
	v_mfma_f32_16x16x32_bf16 v[104:107], v[104:107], v[56:59], v[220:223]
	s_waitcnt lgkmcnt(1)
	v_mfma_f32_16x16x32_bf16 v[168:171], v[140:143], v[0:3], v[216:219]
	v_mfma_f32_16x16x32_bf16 v[172:175], v[140:143], v[20:23], v[224:227]
	v_mfma_f32_16x16x32_bf16 v[176:179], v[140:143], v[36:39], v[212:215]
	v_mfma_f32_16x16x32_bf16 v[140:143], v[140:143], v[56:59], v[220:223]
	v_mfma_f32_16x16x32_bf16 v[72:75], v[68:71], v[4:7], v[72:75]
	v_mfma_f32_16x16x32_bf16 v[76:79], v[68:71], v[16:19], v[76:79]
	v_mfma_f32_16x16x32_bf16 v[80:83], v[68:71], v[32:35], v[80:83]
	v_mfma_f32_16x16x32_bf16 v[64:67], v[68:71], v[48:51], v[64:67]
	v_mfma_f32_16x16x32_bf16 v[68:71], v[88:91], v[4:7], v[92:95]
	v_mfma_f32_16x16x32_bf16 v[92:95], v[88:91], v[16:19], v[96:99]
	v_mfma_f32_16x16x32_bf16 v[96:99], v[88:91], v[32:35], v[100:103]
	v_mfma_f32_16x16x32_bf16 v[84:87], v[88:91], v[48:51], v[84:87]
	v_mfma_f32_16x16x32_bf16 v[88:91], v[108:111], v[4:7], v[112:115]
	v_mfma_f32_16x16x32_bf16 v[100:103], v[108:111], v[16:19], v[132:135]
	v_mfma_f32_16x16x32_bf16 v[112:115], v[108:111], v[32:35], v[136:139]
	v_mfma_f32_16x16x32_bf16 v[104:107], v[108:111], v[48:51], v[104:107]
	s_waitcnt lgkmcnt(0)
	v_mfma_f32_16x16x32_bf16 v[108:111], v[144:147], v[4:7], v[168:171]
	v_mfma_f32_16x16x32_bf16 v[132:135], v[144:147], v[16:19], v[172:175]
	v_mfma_f32_16x16x32_bf16 v[136:139], v[144:147], v[32:35], v[176:179]
	v_mfma_f32_16x16x32_bf16 v[140:143], v[144:147], v[48:51], v[140:143]
	ds_read_b128 v[144:147], v159 offset:38016
	ds_read_b128 v[168:171], v159 offset:38080
	s_waitcnt lgkmcnt(1)
	v_mfma_f32_16x16x32_bf16 v[72:75], v[144:147], v[8:11], v[72:75]
	v_mfma_f32_16x16x32_bf16 v[76:79], v[144:147], v[24:27], v[76:79]
	v_mfma_f32_16x16x32_bf16 v[80:83], v[144:147], v[40:43], v[80:83]
	v_mfma_f32_16x16x32_bf16 v[64:67], v[144:147], v[52:55], v[64:67]
	ds_read_b128 v[144:147], v159 offset:42368
	ds_read_b128 v[172:175], v159 offset:42432
	s_waitcnt lgkmcnt(1)
	v_mfma_f32_16x16x32_bf16 v[176:179], v[144:147], v[8:11], v[68:71]
	s_nop 2
	ds_read_b128 v[68:71], v159 offset:46720
	ds_read_b128 v[188:191], v159 offset:46784
	v_mfma_f32_16x16x32_bf16 v[180:183], v[144:147], v[24:27], v[92:95]
	v_mfma_f32_16x16x32_bf16 v[184:187], v[144:147], v[40:43], v[96:99]
	v_mfma_f32_16x16x32_bf16 v[84:87], v[144:147], v[52:55], v[84:87]
	s_waitcnt lgkmcnt(1)
	v_mfma_f32_16x16x32_bf16 v[88:91], v[68:71], v[8:11], v[88:91]
	v_mfma_f32_16x16x32_bf16 v[144:147], v[68:71], v[24:27], v[100:103]
	v_mfma_f32_16x16x32_bf16 v[192:195], v[68:71], v[40:43], v[112:115]
	v_mfma_f32_16x16x32_bf16 v[196:199], v[68:71], v[52:55], v[104:107]
	ds_read_b128 v[68:71], v159 offset:51072
	ds_read_b128 v[92:95], v159 offset:51136
	s_waitcnt lgkmcnt(1)
	v_mfma_f32_16x16x32_bf16 v[200:203], v[68:71], v[8:11], v[108:111]
	v_mfma_f32_16x16x32_bf16 v[204:207], v[68:71], v[24:27], v[132:135]
	v_mfma_f32_16x16x32_bf16 v[208:211], v[68:71], v[40:43], v[136:139]
	v_mfma_f32_16x16x32_bf16 v[96:99], v[68:71], v[52:55], v[140:143]
	v_mfma_f32_16x16x32_bf16 v[68:71], v[168:171], v[44:47], v[80:83]
	s_nop 2
	v_add_u32_e32 v80, 0x3000, v160
	v_mfma_f32_16x16x32_bf16 v[112:115], v[172:175], v[12:15], v[176:179]
	ds_read2_b32 v[136:137], v80 offset0:64 offset1:196
	v_add_u32_e32 v80, 0x3400, v160
	ds_read2_b32 v[138:139], v80 offset0:72 offset1:204
	s_waitcnt lgkmcnt(2)
	v_mfma_f32_16x16x32_bf16 v[176:179], v[92:95], v[12:15], v[200:203]
	v_add_u32_e32 v80, 0x5200, v160
	ds_read2_b32 v[140:141], v80 offset1:132
	v_add_u32_e32 v80, 0x5600, v160
	v_mfma_f32_16x16x32_bf16 v[104:107], v[168:171], v[12:15], v[72:75]
	ds_read2_b32 v[142:143], v80 offset0:8 offset1:140
	v_add_u32_e32 v80, 0x7200, v160
	s_nop 1
	s_nop 0
	v_add_u32_e32 v72, 0x1000, v160
	ds_read2_b32 v[132:133], v72 offset1:132
	v_add_u32_e32 v72, 0x1400, v160
	v_mfma_f32_16x16x32_bf16 v[100:103], v[168:171], v[28:31], v[76:79]
	ds_read2_b32 v[134:135], v72 offset0:8 offset1:140
	v_exp_f32_e32 v176, v176
	s_nop 0
	v_mfma_f32_16x16x32_bf16 v[108:111], v[172:175], v[28:31], v[180:183]
	v_exp_f32_e32 v177, v177
	v_add_f32_e32 v176, 1.0, v176
	v_rcp_f32_e32 v176, v176
	v_mfma_f32_16x16x32_bf16 v[76:79], v[172:175], v[44:47], v[184:187]
	v_add_f32_e32 v177, 1.0, v177
	v_rcp_f32_e32 v177, v177
	v_mul_f32_e32 v176, v131, v176
	v_mfma_f32_16x16x32_bf16 v[72:75], v[172:175], v[60:63], v[84:87]
	v_exp_f32_e32 v176, v176
	v_mul_f32_e32 v177, v131, v177
	v_exp_f32_e32 v177, v177
	v_mfma_f32_16x16x32_bf16 v[172:175], v[188:191], v[28:31], v[144:147]
	v_add_u32_e32 v85, 0x7600, v160
	s_nop 0
	v_exp_f32_e32 v114, v114
	ds_read2_b32 v[144:145], v80 offset0:64 offset1:196
	v_mov_b32_e32 v80, v179
	v_exp_f32_e32 v84, v80
	v_mfma_f32_16x16x32_bf16 v[64:67], v[168:171], v[60:63], v[64:67]
	ds_read2_b32 v[146:147], v85 offset0:72 offset1:204
	s_nop 0
	v_add_f32_e32 v84, 1.0, v84
	v_rcp_f32_e32 v84, v84
	v_mfma_f32_16x16x32_bf16 v[168:171], v[188:191], v[12:15], v[88:91]
	v_exp_f32_e32 v174, v174
	s_nop 0
	v_exp_f32_e32 v175, v175
	v_mul_f32_e32 v88, v131, v84
	v_exp_f32_e32 v179, v88
	v_mov_b32_e32 v88, v178
	v_exp_f32_e32 v178, v88
	v_mfma_f32_16x16x32_bf16 v[180:183], v[92:95], v[28:31], v[204:207]
	s_nop 0
	v_exp_f32_e32 v170, v170
	v_add_f32_e32 v178, 1.0, v178
	v_rcp_f32_e32 v178, v178
	s_nop 0
	s_nop 2
	s_nop 0
	v_exp_f32_e32 v182, v182
	v_mul_f32_e32 v178, v131, v178
	v_exp_f32_e32 v178, v178
	v_mov_b32_e32 v85, v183
	v_exp_f32_e32 v167, v85
	v_exp_f32_e32 v171, v171
	v_fma_f32 v184, -v178, v178, 1.0 clamp
	v_add_f32_e32 v182, 1.0, v182
	s_nop 0
	v_fma_f32 v183, -v179, v179, 1.0 clamp
	v_rcp_f32_e32 v182, v182
	v_sqrt_f32_e32 v184, v184
	s_nop 0
	v_add_f32_e32 v170, 1.0, v170
	v_add_f32_e32 v167, 1.0, v167
	s_nop 0
	v_exp_f32_e32 v180, v180
	v_rcp_f32_e32 v170, v170
	s_nop 0
	v_rcp_f32_e32 v167, v167
	v_sqrt_f32_e32 v183, v183
	s_nop 0
	v_add_f32_e32 v171, 1.0, v171
	v_exp_f32_e32 v168, v168
	v_exp_f32_e32 v181, v181
	v_rcp_f32_e32 v171, v171
	s_nop 0
	v_mul_f32_e32 v182, v182, v184
	v_fma_f32 v184, -v176, v176, 1.0 clamp
	v_exp_f32_e32 v169, v169
	v_add_f32_e32 v180, 1.0, v180
	s_nop 0
	v_mul_f32_e32 v170, v131, v170
	v_mul_f32_e32 v167, v167, v183
	v_fma_f32 v183, -v177, v177, 1.0 clamp
	v_rcp_f32_e32 v180, v180
	v_sqrt_f32_e32 v184, v184
	v_exp_f32_e32 v170, v170
	v_add_f32_e32 v168, 1.0, v168
	v_add_f32_e32 v181, 1.0, v181
	s_nop 0
	v_mul_f32_e32 v171, v131, v171
	v_rcp_f32_e32 v168, v168
	v_rcp_f32_e32 v181, v181
	v_sqrt_f32_e32 v183, v183
	v_exp_f32_e32 v171, v171
	v_add_f32_e32 v169, 1.0, v169
	v_rcp_f32_e32 v169, v169
	s_nop 0
	v_mul_f32_e32 v180, v180, v184
	v_fma_f32 v184, -v170, v170, 1.0 clamp
	v_exp_f32_e32 v115, v115
	v_add_f32_e32 v174, 1.0, v174
	s_nop 0
	v_mul_f32_e32 v168, v131, v168
	v_mul_f32_e32 v181, v181, v183
	v_fma_f32 v183, -v171, v171, 1.0 clamp
	v_rcp_f32_e32 v174, v174
	v_sqrt_f32_e32 v184, v184
	s_nop 0
	v_exp_f32_e32 v168, v168
	v_add_f32_e32 v114, 1.0, v114
	v_add_f32_e32 v175, 1.0, v175
	s_nop 0
	v_mul_f32_e32 v169, v131, v169
	v_exp_f32_e32 v172, v172
	v_rcp_f32_e32 v114, v114
	s_nop 0
	v_rcp_f32_e32 v175, v175
	v_sqrt_f32_e32 v183, v183
	s_nop 0
	v_exp_f32_e32 v169, v169
	v_add_f32_e32 v115, 1.0, v115
	v_exp_f32_e32 v112, v112
	s_nop 0
	v_exp_f32_e32 v173, v173
	v_rcp_f32_e32 v115, v115
	s_nop 0
	v_exp_f32_e32 v104, v104
	v_mul_f32_e32 v174, v174, v184
	v_fma_f32 v184, -v168, v168, 1.0 clamp
	v_exp_f32_e32 v113, v113
	v_add_f32_e32 v172, 1.0, v172
	s_nop 0
	v_mul_f32_e32 v114, v131, v114
	s_nop 0
	v_mul_f32_e32 v175, v175, v183
	v_fma_f32 v183, -v169, v169, 1.0 clamp
	v_rcp_f32_e32 v172, v172
	v_sqrt_f32_e32 v184, v184
	s_nop 0
	v_exp_f32_e32 v114, v114
	v_add_f32_e32 v112, 1.0, v112
	v_exp_f32_e32 v105, v105
	v_add_f32_e32 v173, 1.0, v173
	s_nop 0
	v_mul_f32_e32 v115, v131, v115
	v_exp_f32_e32 v110, v110
	v_rcp_f32_e32 v112, v112
	s_nop 0
	v_add_f32_e32 v104, 1.0, v104
	v_rcp_f32_e32 v173, v173
	v_sqrt_f32_e32 v183, v183
	s_nop 0
	v_exp_f32_e32 v115, v115
	v_add_f32_e32 v113, 1.0, v113
	v_exp_f32_e32 v106, v106
	v_rcp_f32_e32 v104, v104
	v_exp_f32_e32 v111, v111
	v_rcp_f32_e32 v113, v113
	s_nop 0
	v_mul_f32_e32 v172, v172, v184
	v_fma_f32 v184, -v114, v114, 1.0 clamp
	v_exp_f32_e32 v107, v107
	v_add_f32_e32 v105, 1.0, v105
	v_add_f32_e32 v110, 1.0, v110
	s_nop 0
	v_mul_f32_e32 v112, v131, v112
	v_rcp_f32_e32 v105, v105
	v_mul_f32_e32 v173, v173, v183
	v_fma_f32 v183, -v115, v115, 1.0 clamp
	v_rcp_f32_e32 v110, v110
	v_sqrt_f32_e32 v184, v184
	s_nop 0
	v_exp_f32_e32 v112, v112
	v_add_f32_e32 v106, 1.0, v106
	v_mul_f32_e32 v104, v131, v104
	v_add_f32_e32 v111, 1.0, v111
	s_nop 0
	v_mul_f32_e32 v113, v131, v113
	v_exp_f32_e32 v108, v108
	v_rcp_f32_e32 v106, v106
	s_nop 0
	v_exp_f32_e32 v104, v104
	v_rcp_f32_e32 v111, v111
	v_sqrt_f32_e32 v183, v183
	s_nop 0
	v_exp_f32_e32 v113, v113
	v_add_f32_e32 v107, 1.0, v107
	v_exp_f32_e32 v100, v100
	v_exp_f32_e32 v109, v109
	v_rcp_f32_e32 v107, v107
	v_mul_f32_e32 v105, v131, v105
	v_mul_f32_e32 v110, v110, v184
	v_fma_f32 v184, -v112, v112, 1.0 clamp
	s_nop 0
	v_exp_f32_e32 v105, v105
	v_add_f32_e32 v108, 1.0, v108
	s_nop 0
	v_mul_f32_e32 v106, v131, v106
	v_exp_f32_e32 v101, v101
	v_fma_f32 v186, -v104, v104, 1.0 clamp
	v_mul_f32_e32 v111, v111, v183
	v_fma_f32 v183, -v113, v113, 1.0 clamp
	v_rcp_f32_e32 v108, v108
	v_sqrt_f32_e32 v184, v184
	s_nop 0
	v_exp_f32_e32 v106, v106
	v_add_f32_e32 v100, 1.0, v100
	s_nop 0
	v_add_f32_e32 v109, 1.0, v109
	s_nop 0
	v_mul_f32_e32 v107, v131, v107
	v_exp_f32_e32 v102, v102
	v_rcp_f32_e32 v100, v100
	v_sqrt_f32_e32 v186, v186
	v_rcp_f32_e32 v109, v109
	v_sqrt_f32_e32 v183, v183
	s_nop 0
	v_exp_f32_e32 v107, v107
	v_fma_f32 v185, -v105, v105, 1.0 clamp
	v_exp_f32_e32 v103, v103
	v_add_f32_e32 v101, 1.0, v101
	s_nop 0
	v_mul_f32_e32 v108, v108, v184
	v_fma_f32 v184, -v106, v106, 1.0 clamp
	v_rcp_f32_e32 v101, v101
	v_sqrt_f32_e32 v185, v185
	v_add_f32_e32 v102, 1.0, v102
	s_nop 0
	v_mul_f32_e32 v100, v100, v186
	v_mul_f32_e32 v109, v109, v183
	v_fma_f32 v183, -v107, v107, 1.0 clamp
	v_rcp_f32_e32 v102, v102
	v_sqrt_f32_e32 v184, v184
	s_waitcnt lgkmcnt(3)
	v_mul_f32_e32 v100, v100, v132
	v_add_f32_e32 v103, 1.0, v103
	s_nop 0
	v_fmac_f32_e32 v100, 0, v104
	v_rcp_f32_e32 v103, v103
	v_sqrt_f32_e32 v183, v183
	v_mul_f32_e32 v101, v101, v185
	v_mul_f32_e32 v100, v105, v100
	v_fmac_f32_e32 v100, v101, v133
	v_mul_f32_e32 v102, v102, v184
	v_mul_f32_e32 v100, v106, v100
	s_waitcnt lgkmcnt(2)
	v_fmac_f32_e32 v100, v102, v134
	v_mul_f32_e32 v103, v103, v183
	v_mul_f32_e32 v100, v107, v100
	v_fmac_f32_e32 v100, v103, v135
	v_mul_f32_e32 v100, v112, v100
	v_fmac_f32_e32 v100, v108, v136
	v_mul_f32_e32 v100, v113, v100
	v_fmac_f32_e32 v100, v109, v137
	v_mul_f32_e32 v100, v114, v100
	v_fmac_f32_e32 v100, v110, v138
	v_mul_f32_e32 v100, v115, v100
	v_fmac_f32_e32 v100, v111, v139
	v_mul_f32_e32 v100, v168, v100
	v_mul_f32_e32 v101, v104, v105
	v_fmac_f32_e32 v100, v172, v140
	v_mul_f32_e32 v101, v106, v101
	v_mul_f32_e32 v100, v169, v100
	v_mul_f32_e32 v101, v107, v101
	v_fmac_f32_e32 v100, v173, v141
	v_mul_f32_e32 v101, v101, v112
	v_mul_f32_e32 v100, v170, v100
	v_mul_f32_e32 v101, v113, v101
	v_fmac_f32_e32 v100, v174, v142
	v_mul_f32_e32 v101, v114, v101
	v_mul_f32_e32 v100, v171, v100
	v_mul_f32_e32 v101, v115, v101
	v_fmac_f32_e32 v100, v175, v143
	v_mul_f32_e32 v101, v101, v168
	v_mul_f32_e32 v100, v176, v100
	v_mul_f32_e32 v101, v169, v101
	s_waitcnt lgkmcnt(1)
	v_fmac_f32_e32 v100, v180, v144
	v_mul_f32_e32 v101, v170, v101
	v_mul_f32_e32 v100, v177, v100
	v_mul_f32_e32 v101, v171, v101
	v_fmac_f32_e32 v100, v181, v145
	v_mul_f32_e32 v101, v101, v176
	v_mul_f32_e32 v100, v178, v100
	v_mul_f32_e32 v101, v177, v101
	s_waitcnt lgkmcnt(0)
	v_fmac_f32_e32 v100, v182, v146
	v_mul_f32_e32 v101, v178, v101
	v_mul_f32_e32 v104, v179, v100
	v_fmac_f32_e32 v104, v167, v147
	v_mul_f32_e32 v103, v179, v101
	ds_bpermute_b32 v100, v162, v103
	ds_bpermute_b32 v102, v164, v103
	ds_bpermute_b32 v101, v165, v103
	ds_bpermute_b32 v103, v166, v103
	ds_bpermute_b32 v107, v162, v104
	ds_bpermute_b32 v106, v164, v104
	ds_bpermute_b32 v105, v165, v104
	ds_bpermute_b32 v104, v166, v104
	v_mfma_f32_16x16x32_bf16 v[80:83], v[188:191], v[44:47], v[192:195]
	v_mfma_f32_16x16x32_bf16 v[84:87], v[188:191], v[60:63], v[196:199]
	v_mfma_f32_16x16x32_bf16 v[88:91], v[92:95], v[44:47], v[208:211]
	v_mfma_f32_16x16x32_bf16 v[92:95], v[92:95], v[60:63], v[96:99]
	s_and_saveexec_b64 s[0:1], s[4:5]
	s_cbranch_execz .LBB0_1523
	s_waitcnt lgkmcnt(3)
	v_fmac_f32_e32 v107, 0, v100
	s_waitcnt lgkmcnt(2)
	v_fmac_f32_e32 v106, v107, v102
	s_waitcnt lgkmcnt(1)
	v_fmac_f32_e32 v105, v106, v101
	v_mul_f32_e64 v96, v100, v102
	v_mul_f32_e64 v97, v101, v103
	s_add_i32 s12, s11, s9
	s_waitcnt lgkmcnt(0)
	v_fmac_f32_e32 v104, v105, v103
	v_mad_i64_i32 v[98:99], s[12:13], s12, v163, v[124:125]
	v_pk_mul_f32 v[96:97], v[96:97], v[96:97] op_sel:[0,1] op_sel_hi:[1,0]
	v_lshl_add_u64 v[98:99], v[98:99], 3, s[36:37]
	v_mov_b32_e32 v97, v104
	global_store_dwordx2 v[98:99], v[96:97], off
.LBB0_1523:
	s_or_b64 exec, exec, s[0:1]
	s_nop 3
	s_nop 0
	v_exp_f32_e32 v91, v91
	s_nop 0
	v_exp_f32_e32 v90, v90
	s_nop 0
	v_add_f32_e32 v91, 1.0, v91
	v_rcp_f32_e32 v91, v91
	v_add_f32_e32 v90, 1.0, v90
	v_exp_f32_e32 v95, v95
	v_rcp_f32_e32 v90, v90
	v_mul_f32_e32 v91, v130, v91
	v_exp_f32_e32 v91, v91
	s_nop 0
	v_exp_f32_e32 v89, v89
	s_nop 0
	v_fma_f32 v96, -v91, v91, 1.0 clamp
	v_exp_f32_e32 v88, v88
	v_add_f32_e32 v95, 1.0, v95
	s_nop 0
	v_mul_f32_e32 v90, v130, v90
	s_nop 0
	v_rcp_f32_e32 v95, v95
	v_sqrt_f32_e32 v96, v96
	v_exp_f32_e32 v90, v90
	v_add_f32_e32 v89, 1.0, v89
	v_exp_f32_e32 v94, v94
	v_rcp_f32_e32 v89, v89
	s_nop 0
	v_add_f32_e32 v88, 1.0, v88
	v_exp_f32_e32 v83, v83
	v_rcp_f32_e32 v88, v88
	s_nop 0
	v_mul_f32_e32 v95, v95, v96
	v_fma_f32 v96, -v90, v90, 1.0 clamp
	v_exp_f32_e32 v82, v82
	v_add_f32_e32 v94, 1.0, v94
	s_nop 0
	v_mul_f32_e32 v89, v130, v89
	v_rcp_f32_e32 v94, v94
	v_sqrt_f32_e32 v96, v96
	s_nop 0
	v_exp_f32_e32 v89, v89
	v_add_f32_e32 v83, 1.0, v83
	v_exp_f32_e32 v93, v93
	v_mul_f32_e32 v88, v130, v88
	v_rcp_f32_e32 v83, v83
	s_nop 0
	s_nop 0
	v_exp_f32_e32 v88, v88
	v_add_f32_e32 v82, 1.0, v82
	v_exp_f32_e32 v81, v81
	v_exp_f32_e32 v92, v92
	v_rcp_f32_e32 v82, v82
	s_nop 0
	v_mul_f32_e32 v94, v94, v96
	v_fma_f32 v96, -v89, v89, 1.0 clamp
	v_exp_f32_e32 v80, v80
	v_add_f32_e32 v93, 1.0, v93
	s_nop 0
	v_mul_f32_e32 v83, v130, v83
	v_rcp_f32_e32 v93, v93
	v_sqrt_f32_e32 v96, v96
	v_fma_f32 v97, -v88, v88, 1.0 clamp
	s_nop 0
	v_exp_f32_e32 v83, v83
	v_add_f32_e32 v81, 1.0, v81
	v_add_f32_e32 v92, 1.0, v92
	s_nop 0
	v_exp_f32_e32 v87, v87
	v_mul_f32_e32 v82, v130, v82
	v_rcp_f32_e32 v81, v81
	s_nop 0
	v_rcp_f32_e32 v92, v92
	v_sqrt_f32_e32 v97, v97
	s_nop 0
	v_exp_f32_e32 v82, v82
	v_add_f32_e32 v80, 1.0, v80
	v_exp_f32_e32 v79, v79
	v_exp_f32_e32 v86, v86
	v_rcp_f32_e32 v80, v80
	s_nop 0
	v_mul_f32_e32 v93, v93, v96
	v_fma_f32 v96, -v83, v83, 1.0 clamp
	v_exp_f32_e32 v78, v78
	v_add_f32_e32 v87, 1.0, v87
	s_nop 0
	v_mul_f32_e32 v81, v130, v81
	v_mul_f32_e32 v92, v92, v97
	v_rcp_f32_e32 v87, v87
	v_sqrt_f32_e32 v96, v96
	v_fma_f32 v97, -v82, v82, 1.0 clamp
	s_nop 0
	v_exp_f32_e32 v81, v81
	v_add_f32_e32 v79, 1.0, v79
	v_add_f32_e32 v86, 1.0, v86
	s_nop 0
	v_exp_f32_e32 v85, v85
	v_mul_f32_e32 v80, v130, v80
	v_rcp_f32_e32 v79, v79
	s_nop 0
	v_rcp_f32_e32 v86, v86
	v_sqrt_f32_e32 v97, v97
	s_nop 0
	v_exp_f32_e32 v80, v80
	v_add_f32_e32 v78, 1.0, v78
	v_exp_f32_e32 v77, v77
	v_exp_f32_e32 v84, v84
	v_rcp_f32_e32 v78, v78
	s_nop 0
	v_mul_f32_e32 v95, v95, v147
	v_mul_f32_e32 v87, v87, v96
	v_fma_f32 v96, -v81, v81, 1.0 clamp
	v_exp_f32_e32 v76, v76
	v_add_f32_e32 v85, 1.0, v85
	s_nop 0
	v_mul_f32_e32 v79, v130, v79
	v_fmac_f32_e32 v95, 0, v91
	v_mul_f32_e32 v86, v86, v97
	v_rcp_f32_e32 v85, v85
	v_sqrt_f32_e32 v96, v96
	v_fma_f32 v97, -v80, v80, 1.0 clamp
	s_nop 0
	v_exp_f32_e32 v79, v79
	v_add_f32_e32 v77, 1.0, v77
	v_mul_f32_e32 v95, v90, v95
	v_add_f32_e32 v84, 1.0, v84
	s_nop 0
	v_exp_f32_e32 v75, v75
	v_mul_f32_e32 v78, v130, v78
	v_rcp_f32_e32 v77, v77
	s_nop 0
	v_fmac_f32_e32 v95, v94, v146
	v_rcp_f32_e32 v84, v84
	v_sqrt_f32_e32 v97, v97
	s_nop 0
	v_exp_f32_e32 v78, v78
	v_add_f32_e32 v76, 1.0, v76
	v_exp_f32_e32 v71, v71
	v_mul_f32_e32 v90, v91, v90
	v_mul_f32_e32 v91, v89, v95
	v_exp_f32_e32 v74, v74
	v_rcp_f32_e32 v76, v76
	s_nop 0
	v_fmac_f32_e32 v91, v93, v145
	v_mul_f32_e32 v85, v85, v96
	v_fma_f32 v96, -v79, v79, 1.0 clamp
	v_exp_f32_e32 v70, v70
	v_mul_f32_e32 v89, v89, v90
	v_mul_f32_e32 v90, v88, v91
	v_add_f32_e32 v75, 1.0, v75
	s_nop 0
	v_mul_f32_e32 v77, v130, v77
	s_nop 0
	v_fmac_f32_e32 v90, v92, v144
	v_mul_f32_e32 v84, v84, v97
	v_rcp_f32_e32 v75, v75
	v_sqrt_f32_e32 v96, v96
	v_fma_f32 v97, -v78, v78, 1.0 clamp
	s_nop 0
	v_exp_f32_e32 v77, v77
	v_add_f32_e32 v71, 1.0, v71
	v_exp_f32_e32 v69, v69
	v_mul_f32_e32 v88, v88, v89
	v_mul_f32_e32 v89, v83, v90
	v_add_f32_e32 v74, 1.0, v74
	s_nop 0
	v_exp_f32_e32 v73, v73
	v_mul_f32_e32 v76, v130, v76
	v_rcp_f32_e32 v71, v71
	s_nop 0
	v_fmac_f32_e32 v89, v87, v143
	v_rcp_f32_e32 v74, v74
	v_sqrt_f32_e32 v97, v97
	s_nop 0
	v_exp_f32_e32 v76, v76
	v_add_f32_e32 v70, 1.0, v70
	v_exp_f32_e32 v68, v68
	v_mul_f32_e32 v87, v82, v89
	v_exp_f32_e32 v72, v72
	v_rcp_f32_e32 v70, v70
	v_mul_f32_e32 v83, v83, v88
	v_fmac_f32_e32 v87, v86, v142
	v_mul_f32_e32 v75, v75, v96
	v_fma_f32 v96, -v77, v77, 1.0 clamp
	v_add_f32_e32 v69, 1.0, v69
	v_mul_f32_e32 v82, v82, v83
	v_mul_f32_e32 v83, v81, v87
	v_add_f32_e32 v73, 1.0, v73
	s_nop 0
	v_mul_f32_e32 v71, v130, v71
	v_rcp_f32_e32 v69, v69
	v_fmac_f32_e32 v83, v85, v141
	v_mul_f32_e32 v74, v74, v97
	v_rcp_f32_e32 v73, v73
	v_sqrt_f32_e32 v96, v96
	v_fma_f32 v97, -v76, v76, 1.0 clamp
	s_nop 0
	v_exp_f32_e32 v71, v71
	v_add_f32_e32 v68, 1.0, v68
	v_mul_f32_e32 v81, v81, v82
	v_mul_f32_e32 v82, v80, v83
	v_add_f32_e32 v72, 1.0, v72
	s_nop 0
	v_exp_f32_e32 v67, v67
	v_mul_f32_e32 v70, v130, v70
	v_rcp_f32_e32 v68, v68
	v_fmac_f32_e32 v82, v84, v140
	v_rcp_f32_e32 v72, v72
	v_sqrt_f32_e32 v97, v97
	s_nop 0
	v_exp_f32_e32 v70, v70
	v_mul_f32_e32 v80, v80, v81
	v_mul_f32_e32 v81, v79, v82
	v_exp_f32_e32 v66, v66
	v_mul_f32_e32 v69, v130, v69
	v_fmac_f32_e32 v81, v75, v139
	v_mul_f32_e32 v73, v73, v96
	v_fma_f32 v96, -v71, v71, 1.0 clamp
	s_nop 0
	v_exp_f32_e32 v69, v69
	v_mul_f32_e32 v75, v79, v80
	v_mul_f32_e32 v79, v78, v81
	v_add_f32_e32 v67, 1.0, v67
	s_nop 0
	v_exp_f32_e32 v65, v65
	v_mul_f32_e32 v68, v130, v68
	v_fmac_f32_e32 v79, v74, v138
	v_mul_f32_e32 v72, v72, v97
	v_rcp_f32_e32 v67, v67
	v_sqrt_f32_e32 v96, v96
	v_fma_f32 v97, -v70, v70, 1.0 clamp
	s_nop 0
	v_exp_f32_e32 v68, v68
	v_mul_f32_e32 v74, v78, v75
	v_mul_f32_e32 v75, v77, v79
	v_add_f32_e32 v66, 1.0, v66
	s_nop 0
	v_exp_f32_e32 v64, v64
	v_fmac_f32_e32 v75, v73, v137
	v_rcp_f32_e32 v66, v66
	v_sqrt_f32_e32 v97, v97
	v_fma_f32 v98, -v69, v69, 1.0 clamp
	v_mul_f32_e32 v73, v77, v74
	v_mul_f32_e32 v74, v76, v75
	v_add_f32_e32 v65, 1.0, v65
	s_nop 0
	v_fmac_f32_e32 v74, v72, v136
	v_rcp_f32_e32 v65, v65
	v_sqrt_f32_e32 v98, v98
	v_fma_f32 v99, -v68, v68, 1.0 clamp
	v_mul_f32_e32 v67, v67, v96
	v_mul_f32_e32 v72, v76, v73
	v_mul_f32_e32 v73, v71, v74
	v_add_f32_e32 v64, 1.0, v64
	s_nop 0
	v_fmac_f32_e32 v73, v67, v135
	v_rcp_f32_e32 v64, v64
	v_sqrt_f32_e32 v99, v99
	v_mul_f32_e32 v66, v66, v97
	v_mul_f32_e32 v67, v71, v72
	v_mul_f32_e32 v71, v70, v73
	v_fmac_f32_e32 v71, v66, v134
	v_mul_f32_e32 v65, v65, v98
	v_mul_f32_e32 v66, v70, v67
	v_mul_f32_e32 v67, v69, v71
	v_fmac_f32_e32 v67, v65, v133
	v_mul_f32_e32 v64, v64, v99
	v_mul_f32_e32 v65, v69, v66
	v_mul_f32_e32 v71, v68, v67
	v_fmac_f32_e32 v71, v64, v132
	v_mul_f32_e32 v67, v68, v65
	ds_bpermute_b32 v64, v162, v67
	ds_bpermute_b32 v66, v164, v67
	ds_bpermute_b32 v65, v165, v67
	ds_bpermute_b32 v67, v166, v67
	ds_bpermute_b32 v68, v162, v71
	ds_bpermute_b32 v69, v164, v71
	ds_bpermute_b32 v70, v165, v71
	ds_bpermute_b32 v71, v166, v71
	s_and_saveexec_b64 s[0:1], s[4:5]
	s_cbranch_execz .LBB0_1520
	s_waitcnt lgkmcnt(0)
	v_fmac_f32_e32 v71, 0, v67
	v_fmac_f32_e32 v70, v71, v65
	v_fmac_f32_e32 v69, v70, v66
	v_fmac_f32_e32 v68, v69, v64
	v_mul_f32_e64 v64, v64, v66
	v_mul_f32_e64 v65, v65, v67
	s_add_i32 s11, s10, s11
	v_mad_u64_u32 v[66:67], s[12:13], s11, v163, v[124:125]
	v_pk_mul_f32 v[64:65], v[64:65], v[64:65] op_sel:[0,1] op_sel_hi:[1,0]
	v_lshl_add_u64 v[66:67], v[66:67], 3, s[36:37]
	v_mov_b32_e32 v65, v68
	global_store_dwordx2 v[66:67], v[64:65], off
	s_branch .LBB0_1520

.LBB0_1674:
	v_mov_b32_e32 v224, v172
	v_mov_b32_e32 v225, v172
	v_mov_b32_e32 v226, v172
	v_mov_b32_e32 v227, v172
	v_mov_b32_e32 v228, v173
	v_mov_b32_e32 v229, v173
	v_mov_b32_e32 v230, v173
	v_mov_b32_e32 v231, v173
	v_mov_b32_e32 v232, v174
	v_mov_b32_e32 v233, v174
	v_mov_b32_e32 v234, v174
	v_mov_b32_e32 v235, v174
	v_mov_b32_e32 v236, v175
	v_mov_b32_e32 v237, v175
	v_mov_b32_e32 v238, v175
	v_mov_b32_e32 v239, v175
	s_lshl_b32 s99, s0, 6
	s_add_i32 s15, s0, s12
	v_mad_i64_i32 v[64:65], s[16:17], s15, v197, v[178:179]
	s_addk_i32 s15, 0x210
	s_lshl_b32 s13, s0, 6
	global_load_dword v204, v[64:65], off
	v_mad_u64_u32 v[64:65], s[16:17], s15, v197, v[178:179]
	global_load_dword v203, v[64:65], off
	v_add_u32_e32 v202, s13, v198
	v_mov_b64_e32 v[64:65], s[36:37]
	v_mad_i64_i32 v[64:65], s[16:17], v202, s53, v[64:65]
	v_lshl_add_u64 v[64:65], s[76:77], 1, v[64:65]
	v_lshl_add_u64 v[64:65], v[64:65], 0, v[156:157]
	v_lshl_add_u64 v[66:67], v[64:65], 0, s[74:75]
	v_add_co_u32_e32 v64, vcc, s88, v64
	v_addc_co_u32_e32 v65, vcc, 0, v65, vcc
	global_load_dwordx4 v[68:71], v[64:65], off offset:2560
	s_nop 0
	global_load_dwordx4 v[64:67], v[66:67], off offset:16
	s_add_i32 s0, s0, 1
	v_and_b32_e32 v106, 31, v154
	v_lshrrev_b32_e32 v107, 5, v154
	v_lshlrev_b32_e32 v128, 4, v106
	v_add_u32_e32 v128, 0xf0, v128
	v_lshlrev_b32_e32 v133, 3, v106
	v_add_u32_e32 v133, 0xf0, v133
	v_lshl_add_u32 v129, v107, 2, s99
	v_mov_b32_e32 v132, 0x110
	v_mad_u32_u24 v129, v129, v132, v133
	ds_read_b128 v[72:75], v128
	ds_read_b128 v[88:91], v128 offset:2048
	ds_read_b64 v[92:93], v129 offset:55296
	ds_read_b128 v[76:79], v128 offset:512
	ds_read_b64 v[94:95], v129 offset:55568
	ds_read_b128 v[80:83], v128 offset:1024
	ds_read_b64 v[96:97], v129 offset:55840
	ds_read_b128 v[84:87], v128 offset:1536
	ds_read_b64 v[98:99], v129 offset:56112
	ds_read_b64 v[100:101], v129 offset:56384
	ds_read_b64 v[102:103], v129 offset:56656
	ds_read_b64 v[104:105], v129 offset:56928
	v_and_b32_e32 v130, 3, v107
	v_lshlrev_b32_e32 v130, 4, v130
	v_lshrrev_b32_e32 v131, 2, v107
	v_lshl_add_u32 v106, v131, 2, v130
	v_mad_u32_u24 v131, v106, v132, v133
	v_mov_b32_e32 v132, 0x210
	v_mad_u32_u24 v130, v106, v132, v128
	s_waitcnt lgkmcnt(10)
	v_mov_b64_e32 v[108:109], v[88:89]
	v_mov_b64_e32 v[110:111], v[90:91]
	v_mov_b64_e32 v[112:113], v[88:89]
	v_mov_b64_e32 v[114:115], v[90:91]
	v_mov_b64_e32 v[116:117], v[88:89]
	v_mov_b64_e32 v[118:119], v[90:91]
	v_mov_b64_e32 v[120:121], v[88:89]
	v_mov_b64_e32 v[122:123], v[90:91]
	s_waitcnt lgkmcnt(9)
	v_lshlrev_b32_e32 v124, 16, v92
	v_and_b32_e32 v125, 0xffff0000, v92
	v_lshlrev_b32_e32 v126, 16, v93
	v_and_b32_e32 v127, 0xffff0000, v93
	v_fmac_f32_e32 v108, v124, v72
	v_fmac_f32_e32 v109, v125, v73
	v_fmac_f32_e32 v110, v126, v74
	v_fmac_f32_e32 v111, v127, v75
	s_waitcnt lgkmcnt(7)
	v_lshlrev_b32_e32 v124, 16, v94
	v_and_b32_e32 v125, 0xffff0000, v94
	v_lshlrev_b32_e32 v126, 16, v95
	v_and_b32_e32 v127, 0xffff0000, v95
	v_fmac_f32_e32 v112, v124, v72
	v_fmac_f32_e32 v113, v125, v73
	v_fmac_f32_e32 v114, v126, v74
	v_fmac_f32_e32 v115, v127, v75
	v_fmac_f32_e32 v108, v124, v76
	v_fmac_f32_e32 v109, v125, v77
	v_fmac_f32_e32 v110, v126, v78
	v_fmac_f32_e32 v111, v127, v79
	s_waitcnt lgkmcnt(5)
	v_lshlrev_b32_e32 v124, 16, v96
	v_and_b32_e32 v125, 0xffff0000, v96
	v_lshlrev_b32_e32 v126, 16, v97
	v_and_b32_e32 v127, 0xffff0000, v97
	v_fmac_f32_e32 v116, v124, v72
	v_fmac_f32_e32 v117, v125, v73
	v_fmac_f32_e32 v118, v126, v74
	v_fmac_f32_e32 v119, v127, v75
	v_fmac_f32_e32 v112, v124, v76
	v_fmac_f32_e32 v113, v125, v77
	v_fmac_f32_e32 v114, v126, v78
	v_fmac_f32_e32 v115, v127, v79
	v_fmac_f32_e32 v108, v124, v80
	v_fmac_f32_e32 v109, v125, v81
	v_fmac_f32_e32 v110, v126, v82
	v_fmac_f32_e32 v111, v127, v83
	s_waitcnt lgkmcnt(3)
	v_lshlrev_b32_e32 v124, 16, v98
	v_and_b32_e32 v125, 0xffff0000, v98
	v_lshlrev_b32_e32 v126, 16, v99
	v_and_b32_e32 v127, 0xffff0000, v99
	v_fmac_f32_e32 v120, v124, v72
	v_fmac_f32_e32 v121, v125, v73
	v_fmac_f32_e32 v122, v126, v74
	v_fmac_f32_e32 v123, v127, v75
	v_fmac_f32_e32 v116, v124, v76
	v_fmac_f32_e32 v117, v125, v77
	v_fmac_f32_e32 v118, v126, v78
	v_fmac_f32_e32 v119, v127, v79
	v_fmac_f32_e32 v112, v124, v80
	v_fmac_f32_e32 v113, v125, v81
	v_fmac_f32_e32 v114, v126, v82
	v_fmac_f32_e32 v115, v127, v83
	v_fmac_f32_e32 v108, v124, v84
	v_fmac_f32_e32 v109, v125, v85
	v_fmac_f32_e32 v110, v126, v86
	v_fmac_f32_e32 v111, v127, v87
	s_waitcnt lgkmcnt(2)
	v_lshlrev_b32_e32 v124, 16, v100
	v_and_b32_e32 v125, 0xffff0000, v100
	v_lshlrev_b32_e32 v126, 16, v101
	v_and_b32_e32 v127, 0xffff0000, v101
	v_fmac_f32_e32 v120, v124, v76
	v_fmac_f32_e32 v121, v125, v77
	v_fmac_f32_e32 v122, v126, v78
	v_fmac_f32_e32 v123, v127, v79
	v_fmac_f32_e32 v116, v124, v80
	v_fmac_f32_e32 v117, v125, v81
	v_fmac_f32_e32 v118, v126, v82
	v_fmac_f32_e32 v119, v127, v83
	v_fmac_f32_e32 v112, v124, v84
	v_fmac_f32_e32 v113, v125, v85
	v_fmac_f32_e32 v114, v126, v86
	v_fmac_f32_e32 v115, v127, v87
	s_waitcnt lgkmcnt(1)
	v_lshlrev_b32_e32 v124, 16, v102
	v_and_b32_e32 v125, 0xffff0000, v102
	v_lshlrev_b32_e32 v126, 16, v103
	v_and_b32_e32 v127, 0xffff0000, v103
	v_fmac_f32_e32 v120, v124, v80
	v_fmac_f32_e32 v121, v125, v81
	v_fmac_f32_e32 v122, v126, v82
	v_fmac_f32_e32 v123, v127, v83
	v_fmac_f32_e32 v116, v124, v84
	v_fmac_f32_e32 v117, v125, v85
	v_fmac_f32_e32 v118, v126, v86
	v_fmac_f32_e32 v119, v127, v87
	s_waitcnt lgkmcnt(0)
	v_lshlrev_b32_e32 v124, 16, v104
	v_and_b32_e32 v125, 0xffff0000, v104
	v_lshlrev_b32_e32 v126, 16, v105
	v_and_b32_e32 v127, 0xffff0000, v105
	v_fmac_f32_e32 v120, v124, v84
	v_fmac_f32_e32 v121, v125, v85
	v_fmac_f32_e32 v122, v126, v86
	v_fmac_f32_e32 v123, v127, v87
	ds_write_b128 v130, v[108:111] offset:4096
	ds_write_b128 v130, v[112:115] offset:4624
	ds_write_b128 v130, v[116:119] offset:5152
	ds_write_b128 v130, v[120:123] offset:5680
	v_cvt_pk_bf16_f32 v92, v108, v109
	v_cvt_pk_bf16_f32 v93, v110, v111
	v_cvt_pk_bf16_f32 v94, v112, v113
	v_cvt_pk_bf16_f32 v95, v114, v115
	v_cvt_pk_bf16_f32 v96, v116, v117
	v_cvt_pk_bf16_f32 v97, v118, v119
	v_cvt_pk_bf16_f32 v98, v120, v121
	v_cvt_pk_bf16_f32 v99, v122, v123
	ds_write_b64 v131, v[92:93] offset:37888
	ds_write_b64 v131, v[94:95] offset:38160
	ds_write_b64 v131, v[96:97] offset:38432
	ds_write_b64 v131, v[98:99] offset:38704
	s_waitcnt lgkmcnt(0)
	s_barrier
	ds_read_b128 v[72:75], v192 offset:37888
	ds_read_b128 v[136:139], v192 offset:37952
	s_waitcnt lgkmcnt(1)
	v_mfma_f32_16x16x32_bf16 v[76:79], v[72:75], v[0:3], v[224:227]
	ds_read_b128 v[88:91], v192 offset:42240
	ds_read_b128 v[104:107], v192 offset:46592
	ds_read_b128 v[120:123], v192 offset:50944
	v_mfma_f32_16x16x32_bf16 v[80:83], v[72:75], v[20:23], v[232:235]
	s_cmp_ge_i32 s0, s1
	v_mfma_f32_16x16x32_bf16 v[84:87], v[72:75], v[36:39], v[228:231]
	s_waitcnt vmcnt(5)
	v_mfma_f32_16x16x32_bf16 v[72:75], v[72:75], v[56:59], v[236:239]
	s_waitcnt lgkmcnt(3)
	v_mfma_f32_16x16x32_bf16 v[76:79], v[136:139], v[4:7], v[76:79]
	v_mfma_f32_16x16x32_bf16 v[80:83], v[136:139], v[16:19], v[80:83]
	v_mfma_f32_16x16x32_bf16 v[84:87], v[136:139], v[32:35], v[84:87]
	v_mfma_f32_16x16x32_bf16 v[72:75], v[136:139], v[48:51], v[72:75]
	ds_read_b128 v[136:139], v192 offset:42304
	s_waitcnt lgkmcnt(3)
	v_mfma_f32_16x16x32_bf16 v[92:95], v[88:91], v[0:3], v[224:227]
	v_mfma_f32_16x16x32_bf16 v[96:99], v[88:91], v[20:23], v[232:235]
	v_mfma_f32_16x16x32_bf16 v[100:103], v[88:91], v[36:39], v[228:231]
	v_mfma_f32_16x16x32_bf16 v[88:91], v[88:91], v[56:59], v[236:239]
	s_waitcnt lgkmcnt(0)
	v_mfma_f32_16x16x32_bf16 v[92:95], v[136:139], v[4:7], v[92:95]
	v_mfma_f32_16x16x32_bf16 v[96:99], v[136:139], v[16:19], v[96:99]
	v_mfma_f32_16x16x32_bf16 v[100:103], v[136:139], v[32:35], v[100:103]
	v_mfma_f32_16x16x32_bf16 v[88:91], v[136:139], v[48:51], v[88:91]
	ds_read_b128 v[136:139], v192 offset:46656
	v_mfma_f32_16x16x32_bf16 v[108:111], v[104:107], v[0:3], v[224:227]
	v_mfma_f32_16x16x32_bf16 v[112:115], v[104:107], v[20:23], v[232:235]
	v_mfma_f32_16x16x32_bf16 v[116:119], v[104:107], v[36:39], v[228:231]
	v_mfma_f32_16x16x32_bf16 v[104:107], v[104:107], v[56:59], v[236:239]
	s_waitcnt lgkmcnt(0)
	v_mfma_f32_16x16x32_bf16 v[108:111], v[136:139], v[4:7], v[108:111]
	v_mfma_f32_16x16x32_bf16 v[112:115], v[136:139], v[16:19], v[112:115]
	v_mfma_f32_16x16x32_bf16 v[116:119], v[136:139], v[32:35], v[116:119]
	v_mfma_f32_16x16x32_bf16 v[104:107], v[136:139], v[48:51], v[104:107]
	ds_read_b128 v[136:139], v192 offset:51008
	v_mfma_f32_16x16x32_bf16 v[124:127], v[120:123], v[0:3], v[224:227]
	v_mfma_f32_16x16x32_bf16 v[128:131], v[120:123], v[20:23], v[232:235]
	v_mfma_f32_16x16x32_bf16 v[132:135], v[120:123], v[36:39], v[228:231]
	v_mfma_f32_16x16x32_bf16 v[120:123], v[120:123], v[56:59], v[236:239]
	s_waitcnt lgkmcnt(0)
	v_mfma_f32_16x16x32_bf16 v[124:127], v[136:139], v[4:7], v[124:127]
	v_mfma_f32_16x16x32_bf16 v[128:131], v[136:139], v[16:19], v[128:131]
	v_mfma_f32_16x16x32_bf16 v[132:135], v[136:139], v[32:35], v[132:135]
	v_mfma_f32_16x16x32_bf16 v[120:123], v[136:139], v[48:51], v[120:123]
	ds_read_b128 v[136:139], v192 offset:38016
	s_waitcnt lgkmcnt(0)
	v_mfma_f32_16x16x32_bf16 v[76:79], v[136:139], v[8:11], v[76:79]
	v_mfma_f32_16x16x32_bf16 v[80:83], v[136:139], v[24:27], v[80:83]
	v_mfma_f32_16x16x32_bf16 v[84:87], v[136:139], v[40:43], v[84:87]
	v_mfma_f32_16x16x32_bf16 v[136:139], v[136:139], v[52:55], v[72:75]
	s_nop 2
	ds_read_b128 v[72:75], v192 offset:42368
	s_waitcnt lgkmcnt(0)
	v_mfma_f32_16x16x32_bf16 v[92:95], v[72:75], v[8:11], v[92:95]
	v_mfma_f32_16x16x32_bf16 v[96:99], v[72:75], v[24:27], v[96:99]
	v_mfma_f32_16x16x32_bf16 v[100:103], v[72:75], v[40:43], v[100:103]
	v_mfma_f32_16x16x32_bf16 v[88:91], v[72:75], v[52:55], v[88:91]
	ds_read_b128 v[72:75], v192 offset:46720
	s_waitcnt lgkmcnt(0)
	v_mfma_f32_16x16x32_bf16 v[140:143], v[72:75], v[8:11], v[108:111]
	v_mfma_f32_16x16x32_bf16 v[144:147], v[72:75], v[24:27], v[112:115]
	v_mfma_f32_16x16x32_bf16 v[148:151], v[72:75], v[40:43], v[116:119]
	s_nop 1
	ds_read_b128 v[112:115], v192 offset:38080
	v_mfma_f32_16x16x32_bf16 v[206:209], v[72:75], v[52:55], v[104:107]
	ds_read_b128 v[72:75], v192 offset:51072
	s_waitcnt lgkmcnt(0)
	v_mfma_f32_16x16x32_bf16 v[210:213], v[72:75], v[8:11], v[124:127]
	v_mfma_f32_16x16x32_bf16 v[128:131], v[72:75], v[24:27], v[128:131]
	v_mfma_f32_16x16x32_bf16 v[132:135], v[72:75], v[40:43], v[132:135]
	v_mfma_f32_16x16x32_bf16 v[214:217], v[72:75], v[52:55], v[120:123]
	v_mfma_f32_16x16x32_bf16 v[72:75], v[112:115], v[44:47], v[84:87]
	s_nop 2
	ds_read_b128 v[84:87], v192 offset:42432
	v_mfma_f32_16x16x32_bf16 v[104:107], v[112:115], v[12:15], v[76:79]
	s_nop 2
	s_nop 0
	v_exp_f32_e32 v75, v75
	s_nop 0
	v_mfma_f32_16x16x32_bf16 v[108:111], v[112:115], v[28:31], v[80:83]
	v_exp_f32_e32 v74, v74
	s_nop 0
	v_exp_f32_e32 v107, v107
	s_waitcnt vmcnt(4)
	v_mfma_f32_16x16x32_bf16 v[76:79], v[112:115], v[60:63], v[136:139]
	s_nop 0
	v_exp_f32_e32 v106, v106
	v_add_f32_e32 v107, 1.0, v107
	s_waitcnt lgkmcnt(0)
	v_mfma_f32_16x16x32_bf16 v[112:115], v[84:87], v[12:15], v[92:95]
	v_rcp_f32_e32 v107, v107
	s_nop 0
	v_add_f32_e32 v106, 1.0, v106
	v_mfma_f32_16x16x32_bf16 v[80:83], v[84:87], v[44:47], v[100:103]
	ds_read_b128 v[92:95], v192 offset:46784
	s_nop 2
	s_nop 0
	v_exp_f32_e32 v115, v115
	ds_read_b128 v[100:103], v192 offset:51136
	v_mfma_f32_16x16x32_bf16 v[116:119], v[84:87], v[28:31], v[96:99]
	s_nop 0
	v_add_f32_e32 v115, 1.0, v115
	v_rcp_f32_e32 v115, v115
	v_mfma_f32_16x16x32_bf16 v[84:87], v[84:87], v[60:63], v[88:91]
	v_exp_f32_e32 v114, v114
	s_nop 2
	s_nop 0
	v_mul_f32_e32 v115, v176, v115
	s_waitcnt lgkmcnt(1)
	v_mfma_f32_16x16x32_bf16 v[88:91], v[92:95], v[44:47], v[148:151]
	v_exp_f32_e32 v115, v115
	v_add_f32_e32 v114, 1.0, v114
	v_exp_f32_e32 v119, v119
	s_waitcnt lgkmcnt(0)
	v_mfma_f32_16x16x32_bf16 v[148:151], v[100:103], v[12:15], v[210:213]
	v_rcp_f32_e32 v114, v114
	s_nop 0
	v_exp_f32_e32 v113, v113
	v_mfma_f32_16x16x32_bf16 v[124:127], v[92:95], v[28:31], v[144:147]
	v_add_f32_e32 v119, 1.0, v119
	s_nop 2
	s_nop 0
	v_exp_f32_e32 v148, v148
	v_mov_b32_e32 v145, v151
	v_exp_f32_e32 v145, v145
	v_mfma_f32_16x16x32_bf16 v[120:123], v[92:95], v[12:15], v[140:143]
	v_mov_b32_e32 v146, v150
	v_exp_f32_e32 v146, v146
	v_add_f32_e32 v145, 1.0, v145
	v_rcp_f32_e32 v145, v145
	v_mfma_f32_16x16x32_bf16 v[92:95], v[92:95], v[60:63], v[206:209]
	v_add_f32_e32 v146, 1.0, v146
	v_rcp_f32_e32 v146, v146
	v_mul_f32_e32 v145, v176, v145
	v_mfma_f32_16x16x32_bf16 v[206:209], v[100:103], v[28:31], v[128:131]
	v_exp_f32_e32 v151, v145
	v_mul_f32_e32 v146, v176, v146
	v_mov_b32_e32 v147, v149
	v_exp_f32_e32 v150, v146
	v_fma_f32 v145, -v151, v151, 1.0 clamp
	s_nop 2
	v_mov_b32_e32 v144, v209
	v_exp_f32_e32 v144, v144
	s_nop 0
	v_sqrt_f32_e32 v145, v145
	v_exp_f32_e32 v147, v147
	v_add_f32_e32 v144, 1.0, v144
	v_rcp_f32_e32 v144, v144
	v_fma_f32 v146, -v150, v150, 1.0 clamp
	v_add_f32_e32 v147, 1.0, v147
	s_nop 0
	v_mul_f32_e32 v144, v144, v145
	v_mov_b32_e32 v145, v208
	v_exp_f32_e32 v145, v145
	v_rcp_f32_e32 v147, v147
	v_sqrt_f32_e32 v146, v146
	v_add_f32_e32 v148, 1.0, v148
	v_add_f32_e32 v145, 1.0, v145
	v_rcp_f32_e32 v145, v145
	v_mul_f32_e32 v147, v176, v147
	v_exp_f32_e32 v149, v147
	v_rcp_f32_e32 v148, v148
	v_mul_f32_e32 v145, v145, v146
	v_mov_b32_e32 v146, v207
	v_exp_f32_e32 v146, v146
	v_fma_f32 v147, -v149, v149, 1.0 clamp
	s_nop 0
	v_sqrt_f32_e32 v147, v147
	v_add_f32_e32 v146, 1.0, v146
	v_rcp_f32_e32 v146, v146
	v_mul_f32_e32 v148, v176, v148
	s_nop 0
	v_exp_f32_e32 v148, v148
	v_mul_f32_e32 v146, v146, v147
	v_mov_b32_e32 v147, v206
	v_exp_f32_e32 v123, v123
	v_exp_f32_e32 v147, v147
	v_fma_f32 v152, -v148, v148, 1.0 clamp
	s_nop 0
	v_add_f32_e32 v123, 1.0, v123
	v_add_f32_e32 v147, 1.0, v147
	v_rcp_f32_e32 v123, v123
	v_rcp_f32_e32 v147, v147
	v_sqrt_f32_e32 v152, v152
	s_nop 0
	v_mul_f32_e32 v123, v176, v123
	s_nop 0
	v_mul_f32_e32 v147, v147, v152
	v_exp_f32_e32 v152, v123
	v_exp_f32_e32 v122, v122
	v_exp_f32_e32 v127, v127
	s_nop 0
	v_fma_f32 v123, -v152, v152, 1.0 clamp
	v_add_f32_e32 v122, 1.0, v122
	v_add_f32_e32 v127, 1.0, v127
	s_nop 0
	v_rcp_f32_e32 v122, v122
	v_rcp_f32_e32 v127, v127
	v_sqrt_f32_e32 v123, v123
	v_exp_f32_e32 v121, v121
	v_mul_f32_e32 v122, v176, v122
	s_nop 0
	v_mul_f32_e32 v123, v127, v123
	v_exp_f32_e32 v127, v122
	v_add_f32_e32 v121, 1.0, v121
	v_exp_f32_e32 v126, v126
	v_rcp_f32_e32 v121, v121
	s_nop 0
	v_exp_f32_e32 v120, v120
	v_fma_f32 v122, -v127, v127, 1.0 clamp
	v_add_f32_e32 v126, 1.0, v126
	s_nop 0
	v_mul_f32_e32 v121, v176, v121
	v_rcp_f32_e32 v126, v126
	v_sqrt_f32_e32 v122, v122
	s_nop 0
	v_exp_f32_e32 v121, v121
	v_add_f32_e32 v120, 1.0, v120
	v_exp_f32_e32 v125, v125
	v_rcp_f32_e32 v120, v120
	v_mul_f32_e32 v122, v126, v122
	v_fma_f32 v126, -v121, v121, 1.0 clamp
	v_add_f32_e32 v125, 1.0, v125
	s_nop 0
	v_mul_f32_e32 v120, v176, v120
	v_rcp_f32_e32 v125, v125
	v_sqrt_f32_e32 v126, v126
	s_nop 0
	v_exp_f32_e32 v120, v120
	v_exp_f32_e32 v124, v124
	v_mul_f32_e32 v125, v125, v126
	v_mul_f32_e32 v114, v176, v114
	v_fma_f32 v126, -v120, v120, 1.0 clamp
	v_add_f32_e32 v124, 1.0, v124
	s_nop 0
	v_rcp_f32_e32 v124, v124
	v_sqrt_f32_e32 v126, v126
	v_rcp_f32_e32 v119, v119
	s_nop 0
	v_exp_f32_e32 v114, v114
	v_mul_f32_e32 v124, v124, v126
	v_fma_f32 v126, -v115, v115, 1.0 clamp
	s_nop 0
	v_sqrt_f32_e32 v126, v126
	v_add_f32_e32 v113, 1.0, v113
	v_exp_f32_e32 v118, v118
	v_rcp_f32_e32 v113, v113
	s_nop 0
	v_exp_f32_e32 v112, v112
	v_mul_f32_e32 v119, v119, v126
	v_fma_f32 v126, -v114, v114, 1.0 clamp
	v_add_f32_e32 v118, 1.0, v118
	s_nop 0
	v_mul_f32_e32 v113, v176, v113
	v_rcp_f32_e32 v118, v118
	v_sqrt_f32_e32 v126, v126
	s_nop 0
	v_exp_f32_e32 v113, v113
	v_add_f32_e32 v112, 1.0, v112
	v_exp_f32_e32 v117, v117
	v_rcp_f32_e32 v112, v112
	v_mul_f32_e32 v118, v118, v126
	v_fma_f32 v126, -v113, v113, 1.0 clamp
	v_add_f32_e32 v117, 1.0, v117
	s_nop 0
	v_mul_f32_e32 v112, v176, v112
	v_rcp_f32_e32 v117, v117
	v_sqrt_f32_e32 v126, v126
	s_nop 0
	v_exp_f32_e32 v112, v112
	v_exp_f32_e32 v116, v116
	v_mul_f32_e32 v117, v117, v126
	v_mul_f32_e32 v107, v176, v107
	v_fma_f32 v126, -v112, v112, 1.0 clamp
	v_add_f32_e32 v116, 1.0, v116
	s_nop 0
	v_rcp_f32_e32 v116, v116
	v_sqrt_f32_e32 v126, v126
	v_exp_f32_e32 v107, v107
	v_exp_f32_e32 v111, v111
	v_rcp_f32_e32 v106, v106
	s_nop 0
	v_exp_f32_e32 v105, v105
	v_mul_f32_e32 v116, v116, v126
	v_fma_f32 v126, -v107, v107, 1.0 clamp
	v_add_f32_e32 v111, 1.0, v111
	s_nop 0
	v_mul_f32_e32 v106, v176, v106
	v_rcp_f32_e32 v111, v111
	v_sqrt_f32_e32 v126, v126
	s_nop 0
	v_exp_f32_e32 v106, v106
	v_add_f32_e32 v105, 1.0, v105
	v_exp_f32_e32 v110, v110
	v_rcp_f32_e32 v105, v105
	s_nop 0
	v_exp_f32_e32 v104, v104
	v_mul_f32_e32 v111, v111, v126
	v_fma_f32 v126, -v106, v106, 1.0 clamp
	v_add_f32_e32 v110, 1.0, v110
	s_nop 0
	v_mul_f32_e32 v105, v176, v105
	v_rcp_f32_e32 v110, v110
	v_sqrt_f32_e32 v126, v126
	s_nop 0
	v_exp_f32_e32 v105, v105
	v_add_f32_e32 v104, 1.0, v104
	v_exp_f32_e32 v109, v109
	v_rcp_f32_e32 v104, v104
	v_mul_f32_e32 v110, v110, v126
	v_fma_f32 v126, -v105, v105, 1.0 clamp
	v_add_f32_e32 v109, 1.0, v109
	s_nop 0
	v_mul_f32_e32 v104, v176, v104
	v_rcp_f32_e32 v109, v109
	v_sqrt_f32_e32 v126, v126
	s_nop 0
	v_exp_f32_e32 v104, v104
	v_exp_f32_e32 v108, v108
	v_mul_f32_e32 v109, v109, v126
	v_add_u32_e32 v128, 0x1000, v193
	v_fma_f32 v126, -v104, v104, 1.0 clamp
	v_add_f32_e32 v108, 1.0, v108
	s_nop 0
	ds_read2_b32 v[128:129], v128 offset1:132
	v_rcp_f32_e32 v108, v108
	v_sqrt_f32_e32 v126, v126
	v_add_u32_e32 v130, 0x1400, v193
	ds_read2_b32 v[130:131], v130 offset0:8 offset1:140
	v_mfma_f32_16x16x32_bf16 v[96:99], v[100:103], v[44:47], v[132:135]
	v_mul_f32_e32 v108, v108, v126
	s_waitcnt lgkmcnt(1)
	v_mul_f32_e32 v108, v108, v128
	v_mul_f32_e32 v109, v109, v129
	v_add_u32_e32 v132, 0x3000, v193
	ds_read2_b32 v[132:133], v132 offset0:64 offset1:196
	v_add_u32_e32 v134, 0x3400, v193
	ds_read2_b32 v[134:135], v134 offset0:72 offset1:204
	v_fma_f32 v126, 0, v104, v108
	v_add_u32_e32 v136, 0x5200, v193
	s_waitcnt lgkmcnt(2)
	v_mul_f32_e32 v110, v110, v130
	v_fma_f32 v126, v105, v126, v109
	v_mul_f32_e32 v153, v104, v105
	ds_read2_b32 v[136:137], v136 offset1:132
	v_mul_f32_e32 v111, v111, v131
	v_fma_f32 v126, v106, v126, v110
	v_mul_f32_e32 v153, v106, v153
	v_add_u32_e32 v138, 0x5600, v193
	s_waitcnt lgkmcnt(2)
	v_mul_f32_e32 v116, v116, v132
	v_fma_f32 v126, v107, v126, v111
	v_mul_f32_e32 v153, v107, v153
	ds_read2_b32 v[138:139], v138 offset0:8 offset1:140
	v_mul_f32_e32 v117, v117, v133
	v_fma_f32 v126, v112, v126, v116
	v_mul_f32_e32 v153, v153, v112
	v_add_u32_e32 v140, 0x7200, v193
	s_waitcnt lgkmcnt(2)
	v_mul_f32_e32 v118, v118, v134
	v_fma_f32 v126, v113, v126, v117
	v_mul_f32_e32 v153, v113, v153
	ds_read2_b32 v[140:141], v140 offset0:64 offset1:196
	v_mul_f32_e32 v119, v119, v135
	v_fma_f32 v126, v114, v126, v118
	v_mul_f32_e32 v153, v114, v153
	v_add_u32_e32 v142, 0x7600, v193
	s_waitcnt lgkmcnt(2)
	v_mul_f32_e32 v124, v124, v136
	v_fma_f32 v126, v115, v126, v119
	v_mul_f32_e32 v153, v115, v153
	ds_read2_b32 v[142:143], v142 offset0:72 offset1:204
	v_mul_f32_e32 v125, v125, v137
	v_fma_f32 v126, v120, v126, v124
	v_mul_f32_e32 v153, v153, v120
	s_waitcnt lgkmcnt(2)
	v_mul_f32_e32 v122, v122, v138
	v_fma_f32 v126, v121, v126, v125
	v_mul_f32_e32 v153, v121, v153
	v_mul_f32_e32 v123, v123, v139
	v_fma_f32 v126, v127, v126, v122
	v_mul_f32_e32 v153, v127, v153
	s_nop 0
	s_waitcnt lgkmcnt(1)
	v_mul_f32_e32 v147, v147, v140
	v_fma_f32 v126, v152, v126, v123
	v_mul_f32_e32 v153, v152, v153
	v_exp_f32_e32 v99, v99
	v_mul_f32_e32 v146, v146, v141
	v_fma_f32 v126, v148, v126, v147
	v_mul_f32_e32 v153, v153, v148
	s_waitcnt lgkmcnt(0)
	v_mul_f32_e32 v145, v145, v142
	v_fma_f32 v126, v149, v126, v146
	v_mul_f32_e32 v153, v149, v153
	v_mul_f32_e32 v144, v144, v143
	v_fma_f32 v126, v150, v126, v145
	v_mul_f32_e32 v153, v150, v153
	v_fma_f32 v126, v151, v126, v144
	v_mul_f32_e32 v153, v151, v153
	v_add_f32_e32 v99, 1.0, v99
	ds_bpermute_b32 v205, v196, v153
	ds_bpermute_b32 v207, v196, v126
	v_rcp_f32_e32 v99, v99
	s_nop 0
	v_mfma_f32_16x16x32_bf16 v[100:103], v[100:103], v[60:63], v[214:217]
	ds_bpermute_b32 v206, v199, v153
	ds_bpermute_b32 v208, v199, v126
	v_exp_f32_e32 v98, v98
	ds_bpermute_b32 v153, v200, v153
	ds_bpermute_b32 v126, v200, v126
	v_mul_f32_e32 v99, v177, v99
	s_waitcnt vmcnt(3) lgkmcnt(4)
	v_fmac_f32_e32 v207, v204, v205
	s_nop 0
	v_exp_f32_e32 v99, v99
	v_add_f32_e32 v98, 1.0, v98
	v_cndmask_b32_e64 v204, v204, v207, s[6:7]
	s_waitcnt lgkmcnt(2)
	v_fmac_f32_e32 v208, v207, v206
	v_exp_f32_e32 v103, v103
	v_rcp_f32_e32 v98, v98
	s_nop 0
	v_cndmask_b32_e64 v204, v204, v208, s[4:5]
	s_waitcnt lgkmcnt(0)
	v_fmac_f32_e32 v126, v208, v153
	v_exp_f32_e32 v97, v97
	v_cndmask_b32_e64 v126, v204, v126, s[10:11]
	v_fmac_f32_e32 v108, v104, v126
	v_fma_f32 v104, -v99, v99, 1.0 clamp
	v_add_f32_e32 v103, 1.0, v103
	s_nop 0
	v_mul_f32_e32 v98, v177, v98
	v_rcp_f32_e32 v103, v103
	v_sqrt_f32_e32 v104, v104
	s_nop 0
	v_exp_f32_e32 v98, v98
	v_add_f32_e32 v97, 1.0, v97
	v_exp_f32_e32 v102, v102
	v_rcp_f32_e32 v97, v97
	s_nop 0
	v_exp_f32_e32 v96, v96
	v_mul_f32_e32 v103, v103, v104
	v_fma_f32 v104, -v98, v98, 1.0 clamp
	v_add_f32_e32 v102, 1.0, v102
	s_nop 0
	v_mul_f32_e32 v97, v177, v97
	v_rcp_f32_e32 v102, v102
	v_sqrt_f32_e32 v104, v104
	s_nop 0
	v_exp_f32_e32 v97, v97
	v_add_f32_e32 v96, 1.0, v96
	v_exp_f32_e32 v101, v101
	v_rcp_f32_e32 v96, v96
	s_nop 0
	v_exp_f32_e32 v91, v91
	v_mul_f32_e32 v102, v102, v104
	v_fma_f32 v104, -v97, v97, 1.0 clamp
	v_add_f32_e32 v101, 1.0, v101
	s_nop 0
	v_mul_f32_e32 v96, v177, v96
	v_rcp_f32_e32 v101, v101
	v_sqrt_f32_e32 v104, v104
	s_nop 0
	v_exp_f32_e32 v96, v96
	v_add_f32_e32 v91, 1.0, v91
	v_exp_f32_e32 v100, v100
	v_rcp_f32_e32 v91, v91
	s_nop 0
	v_exp_f32_e32 v90, v90
	v_mul_f32_e32 v101, v101, v104
	v_fma_f32 v104, -v96, v96, 1.0 clamp
	v_add_f32_e32 v100, 1.0, v100
	s_nop 0
	v_mul_f32_e32 v91, v177, v91
	v_rcp_f32_e32 v100, v100
	v_sqrt_f32_e32 v104, v104
	s_nop 0
	v_exp_f32_e32 v91, v91
	v_add_f32_e32 v90, 1.0, v90
	v_exp_f32_e32 v95, v95
	v_rcp_f32_e32 v90, v90
	s_nop 0
	v_exp_f32_e32 v89, v89
	v_mul_f32_e32 v100, v100, v104
	v_fma_f32 v104, -v91, v91, 1.0 clamp
	v_add_f32_e32 v95, 1.0, v95
	s_nop 0
	v_mul_f32_e32 v90, v177, v90
	v_rcp_f32_e32 v95, v95
	v_sqrt_f32_e32 v104, v104
	s_nop 0
	v_exp_f32_e32 v90, v90
	v_add_f32_e32 v89, 1.0, v89
	v_exp_f32_e32 v94, v94
	v_rcp_f32_e32 v89, v89
	s_nop 0
	v_exp_f32_e32 v88, v88
	v_mul_f32_e32 v95, v95, v104
	v_fma_f32 v104, -v90, v90, 1.0 clamp
	v_add_f32_e32 v94, 1.0, v94
	s_nop 0
	v_mul_f32_e32 v89, v177, v89
	v_rcp_f32_e32 v94, v94
	v_sqrt_f32_e32 v104, v104
	s_nop 0
	v_exp_f32_e32 v89, v89
	v_add_f32_e32 v88, 1.0, v88
	v_exp_f32_e32 v93, v93
	v_rcp_f32_e32 v88, v88
	s_nop 0
	v_exp_f32_e32 v83, v83
	v_mul_f32_e32 v94, v94, v104
	v_fma_f32 v104, -v89, v89, 1.0 clamp
	v_add_f32_e32 v93, 1.0, v93
	s_nop 0
	v_mul_f32_e32 v88, v177, v88
	v_rcp_f32_e32 v93, v93
	v_sqrt_f32_e32 v104, v104
	s_nop 0
	v_exp_f32_e32 v88, v88
	v_add_f32_e32 v83, 1.0, v83
	v_exp_f32_e32 v92, v92
	v_rcp_f32_e32 v83, v83
	s_nop 0
	v_exp_f32_e32 v82, v82
	v_mul_f32_e32 v93, v93, v104
	v_fma_f32 v104, -v88, v88, 1.0 clamp
	v_add_f32_e32 v92, 1.0, v92
	s_nop 0
	v_mul_f32_e32 v83, v177, v83
	v_rcp_f32_e32 v92, v92
	v_sqrt_f32_e32 v104, v104
	s_nop 0
	v_exp_f32_e32 v83, v83
	v_add_f32_e32 v82, 1.0, v82
	v_exp_f32_e32 v87, v87
	v_rcp_f32_e32 v82, v82
	s_nop 0
	v_exp_f32_e32 v81, v81
	v_mul_f32_e32 v92, v92, v104
	v_fma_f32 v104, -v83, v83, 1.0 clamp
	v_add_f32_e32 v87, 1.0, v87
	s_nop 0
	v_mul_f32_e32 v82, v177, v82
	v_rcp_f32_e32 v87, v87
	v_sqrt_f32_e32 v104, v104
	s_nop 0
	v_exp_f32_e32 v82, v82
	v_add_f32_e32 v81, 1.0, v81
	v_exp_f32_e32 v86, v86
	v_rcp_f32_e32 v81, v81
	s_nop 0
	v_exp_f32_e32 v80, v80
	v_mul_f32_e32 v87, v87, v104
	v_fma_f32 v104, -v82, v82, 1.0 clamp
	v_add_f32_e32 v86, 1.0, v86
	s_nop 0
	v_mul_f32_e32 v81, v177, v81
	v_rcp_f32_e32 v86, v86
	v_sqrt_f32_e32 v104, v104
	s_nop 0
	v_exp_f32_e32 v81, v81
	v_exp_f32_e32 v85, v85
	v_add_f32_e32 v80, 1.0, v80
	v_rcp_f32_e32 v80, v80
	v_mul_f32_e32 v86, v86, v104
	v_fma_f32 v104, -v81, v81, 1.0 clamp
	v_add_f32_e32 v85, 1.0, v85
	s_nop 0
	v_rcp_f32_e32 v85, v85
	v_sqrt_f32_e32 v104, v104
	v_mul_f32_e32 v80, v177, v80
	s_nop 0
	v_exp_f32_e32 v80, v80
	v_exp_f32_e32 v84, v84
	v_add_f32_e32 v75, 1.0, v75
	v_rcp_f32_e32 v75, v75
	v_mul_f32_e32 v85, v85, v104
	v_mul_f32_e32 v104, v85, v133
	v_fma_f32 v85, -v80, v80, 1.0 clamp
	v_add_f32_e32 v84, 1.0, v84
	s_nop 0
	v_rcp_f32_e32 v84, v84
	v_sqrt_f32_e32 v85, v85
	v_mul_f32_e32 v75, v177, v75
	s_nop 0
	v_exp_f32_e32 v75, v75
	v_add_f32_e32 v74, 1.0, v74
	v_exp_f32_e32 v79, v79
	v_rcp_f32_e32 v74, v74
	s_nop 0
	v_exp_f32_e32 v73, v73
	v_mul_f32_e32 v84, v84, v85
	v_fmac_f32_e32 v109, v105, v108
	v_mul_f32_e32 v105, v84, v132
	v_fma_f32 v84, -v75, v75, 1.0 clamp
	v_add_f32_e32 v79, 1.0, v79
	s_nop 0
	v_mul_f32_e32 v74, v177, v74
	v_rcp_f32_e32 v79, v79
	v_sqrt_f32_e32 v84, v84
	s_nop 0
	v_exp_f32_e32 v74, v74
	v_add_f32_e32 v73, 1.0, v73
	v_exp_f32_e32 v78, v78
	v_rcp_f32_e32 v73, v73
	s_nop 0
	v_exp_f32_e32 v72, v72
	v_mul_f32_e32 v79, v79, v84
	v_fma_f32 v84, -v74, v74, 1.0 clamp
	v_add_f32_e32 v78, 1.0, v78
	s_nop 0
	v_mul_f32_e32 v73, v177, v73
	v_rcp_f32_e32 v78, v78
	v_sqrt_f32_e32 v84, v84
	s_nop 0
	v_exp_f32_e32 v73, v73
	v_add_f32_e32 v72, 1.0, v72
	v_exp_f32_e32 v77, v77
	v_rcp_f32_e32 v72, v72
	v_mul_f32_e32 v78, v78, v84
	v_fma_f32 v84, -v73, v73, 1.0 clamp
	v_add_f32_e32 v77, 1.0, v77
	s_nop 0
	v_mul_f32_e32 v72, v177, v72
	v_rcp_f32_e32 v77, v77
	v_sqrt_f32_e32 v84, v84
	s_nop 0
	v_exp_f32_e32 v72, v72
	v_exp_f32_e32 v76, v76
	v_mul_f32_e32 v77, v77, v84
	v_mul_f32_e32 v103, v103, v143
	v_fma_f32 v84, -v72, v72, 1.0 clamp
	v_add_f32_e32 v76, 1.0, v76
	s_nop 0
	v_rcp_f32_e32 v76, v76
	v_sqrt_f32_e32 v84, v84
	v_mul_f32_e32 v102, v102, v142
	v_mul_f32_e32 v101, v101, v141
	v_mul_f32_e32 v85, v99, v98
	v_mul_f32_e32 v76, v76, v84
	v_fma_f32 v84, 0, v99, v103
	v_fma_f32 v84, v98, v84, v102
	v_mul_f32_e32 v100, v100, v140
	v_fma_f32 v84, v97, v84, v101
	v_mul_f32_e32 v85, v97, v85
	v_mul_f32_e32 v95, v95, v139
	v_fma_f32 v84, v96, v84, v100
	v_mul_f32_e32 v85, v96, v85
	v_mul_f32_e32 v94, v94, v138
	v_fma_f32 v84, v91, v84, v95
	v_mul_f32_e32 v85, v91, v85
	v_mul_f32_e32 v93, v93, v137
	v_fma_f32 v84, v90, v84, v94
	v_mul_f32_e32 v85, v90, v85
	v_mul_f32_e32 v92, v92, v136
	v_fma_f32 v84, v89, v84, v93
	v_mul_f32_e32 v85, v89, v85
	v_mul_f32_e32 v87, v87, v135
	v_fma_f32 v84, v88, v84, v92
	v_mul_f32_e32 v85, v88, v85
	v_mul_f32_e32 v86, v86, v134
	v_fma_f32 v84, v83, v84, v87
	v_mul_f32_e32 v85, v83, v85
	v_fma_f32 v84, v82, v84, v86
	v_mul_f32_e32 v85, v82, v85
	v_fma_f32 v84, v81, v84, v104
	v_mul_f32_e32 v85, v81, v85
	v_mul_f32_e32 v79, v79, v131
	v_fma_f32 v84, v80, v84, v105
	v_mul_f32_e32 v85, v80, v85
	v_mul_f32_e32 v78, v78, v130
	v_fma_f32 v84, v75, v84, v79
	v_mul_f32_e32 v85, v75, v85
	v_fmac_f32_e32 v110, v106, v109
	v_mul_f32_e32 v77, v77, v129
	v_fma_f32 v84, v74, v84, v78
	v_mul_f32_e32 v85, v74, v85
	v_fmac_f32_e32 v111, v107, v110
	v_mul_f32_e32 v76, v76, v128
	v_fma_f32 v84, v73, v84, v77
	v_mul_f32_e32 v85, v73, v85
	v_fmac_f32_e32 v116, v112, v111
	v_fma_f32 v84, v72, v84, v76
	v_mul_f32_e32 v85, v72, v85
	v_fmac_f32_e32 v117, v113, v116
	ds_bpermute_b32 v106, v199, v85
	ds_bpermute_b32 v107, v200, v85
	ds_bpermute_b32 v85, v201, v85
	ds_bpermute_b32 v112, v199, v84
	ds_bpermute_b32 v113, v200, v84
	ds_bpermute_b32 v84, v201, v84
	v_fmac_f32_e32 v118, v114, v117
	v_fmac_f32_e32 v119, v115, v118
	v_fmac_f32_e32 v124, v120, v119
	v_fmac_f32_e32 v125, v121, v124
	s_waitcnt vmcnt(2) lgkmcnt(0)
	v_fmac_f32_e32 v84, v203, v85
	v_cndmask_b32_e64 v85, v203, v84, s[4:5]
	v_fmac_f32_e32 v113, v84, v107
	v_cndmask_b32_e64 v84, v85, v113, s[6:7]
	v_fmac_f32_e32 v112, v113, v106
	v_cndmask_b32_e64 v84, v84, v112, s[8:9]
	v_fmac_f32_e32 v103, v99, v84
	v_fmac_f32_e32 v102, v98, v103
	v_fmac_f32_e32 v101, v97, v102
	v_fmac_f32_e32 v100, v96, v101
	v_fmac_f32_e32 v95, v91, v100
	v_fmac_f32_e32 v94, v90, v95
	v_fmac_f32_e32 v93, v89, v94
	v_fmac_f32_e32 v92, v88, v93
	v_fmac_f32_e32 v87, v83, v92
	v_fmac_f32_e32 v86, v82, v87
	v_fmac_f32_e32 v104, v81, v86
	v_fmac_f32_e32 v105, v80, v104
	v_fmac_f32_e32 v79, v75, v105
	v_fmac_f32_e32 v78, v74, v79
	v_fmac_f32_e32 v77, v73, v78
	v_fmac_f32_e32 v76, v72, v77
	v_add_f32_e32 v88, v108, v76
	v_add_f32_e32 v89, v109, v77
	ds_write2_b32 v194, v88, v89 offset1:132
	s_waitcnt vmcnt(1)
	v_lshlrev_b32_e32 v88, 16, v68
	v_and_b32_e32 v89, 0xffff0000, v68
	v_mul_f32_e32 v68, 0xbfb8aa3b, v88
	v_exp_f32_e32 v68, v68
	v_fmac_f32_e32 v122, v127, v125
	v_add_f32_e32 v84, v110, v78
	v_add_f32_e32 v85, v111, v79
	v_add_f32_e32 v68, 1.0, v68
	v_rcp_f32_e32 v90, v68
	v_mul_f32_e32 v68, 0xbfb8aa3b, v89
	v_exp_f32_e32 v68, v68
	v_add_f32_e32 v80, v118, v86
	v_add_u32_e32 v86, 0x400, v194
	v_fmac_f32_e32 v123, v152, v122
	v_add_f32_e32 v82, v116, v105
	v_add_f32_e32 v83, v117, v104
	ds_write2_b32 v86, v84, v85 offset0:8 offset1:140
	v_add_u32_e32 v84, 0x2000, v194
	v_fmac_f32_e32 v147, v148, v123
	v_add_f32_e32 v81, v119, v87
	ds_write2_b32 v84, v82, v83 offset0:64 offset1:196
	v_add_u32_e32 v82, 0x2400, v194
	v_fmac_f32_e32 v146, v149, v147
	v_add_f32_e32 v78, v124, v92
	v_add_f32_e32 v79, v125, v93
	ds_write2_b32 v82, v80, v81 offset0:72 offset1:204
	v_add_u32_e32 v80, 0x4200, v194
	v_add_f32_e32 v68, 1.0, v68
	v_fmac_f32_e32 v145, v150, v146
	v_add_f32_e32 v76, v94, v122
	v_add_f32_e32 v77, v95, v123
	ds_write2_b32 v80, v78, v79 offset1:132
	v_add_u32_e32 v78, 0x4600, v194
	v_rcp_f32_e32 v91, v68
	v_fmac_f32_e32 v144, v151, v145
	v_add_f32_e32 v74, v100, v147
	v_add_f32_e32 v75, v101, v146
	ds_write2_b32 v78, v76, v77 offset0:8 offset1:140
	v_add_u32_e32 v76, 0x6200, v194
	v_add_f32_e32 v72, v102, v145
	v_add_f32_e32 v73, v103, v144
	ds_write2_b32 v76, v74, v75 offset0:64 offset1:196
	v_add_u32_e32 v74, 0x6600, v194
	ds_write2_b32 v74, v72, v73 offset0:72 offset1:204
	s_waitcnt lgkmcnt(0)
	s_barrier
	ds_read_b128 v[72:75], v186
	ds_read_b128 v[76:79], v186 offset:16
	ds_read_b128 v[80:83], v186 offset:32
	ds_read_b128 v[84:87], v186 offset:48
	v_mul_f32_e64 v88, v90, v88
	v_mul_f32_e64 v89, v91, v89
	s_waitcnt lgkmcnt(3)
	v_mul_f32_e64 v72, v88, v72
	v_mul_f32_e64 v73, v89, v73
	s_nop 0
	v_cvt_pk_bf16_f32 v68, v72, v73
	s_waitcnt vmcnt(0)
	v_lshlrev_b32_e32 v72, 16, v64
	v_and_b32_e32 v73, 0xffff0000, v64
	v_mul_f32_e32 v64, 0xbfb8aa3b, v72
	v_exp_f32_e32 v64, v64
	s_nop 0
	v_add_f32_e32 v64, 1.0, v64
	v_rcp_f32_e32 v88, v64
	v_mul_f32_e32 v64, 0xbfb8aa3b, v73
	v_exp_f32_e32 v64, v64
	s_nop 0
	v_add_f32_e32 v64, 1.0, v64
	v_rcp_f32_e32 v89, v64
	s_nop 0
	v_mul_f32_e64 v72, v88, v72
	v_mul_f32_e64 v73, v89, v73
	s_waitcnt lgkmcnt(1)
	v_mul_f32_e64 v72, v72, v80
	v_mul_f32_e64 v73, v73, v81
	s_nop 0
	v_cvt_pk_bf16_f32 v64, v72, v73
	v_lshlrev_b32_e32 v72, 16, v69
	v_and_b32_e32 v73, 0xffff0000, v69
	v_mul_f32_e32 v69, 0xbfb8aa3b, v72
	v_exp_f32_e32 v69, v69
	s_nop 0
	v_add_f32_e32 v69, 1.0, v69
	v_rcp_f32_e32 v80, v69
	v_mul_f32_e32 v69, 0xbfb8aa3b, v73
	v_exp_f32_e32 v69, v69
	s_nop 0
	v_add_f32_e32 v69, 1.0, v69
	v_rcp_f32_e32 v81, v69
	s_nop 0
	v_mul_f32_e64 v72, v80, v72
	v_mul_f32_e64 v73, v81, v73
	s_nop 0
	v_mul_f32_e64 v72, v72, v74
	v_mul_f32_e64 v73, v73, v75
	s_nop 0
	v_cvt_pk_bf16_f32 v69, v72, v73
	v_lshlrev_b32_e32 v72, 16, v65
	v_and_b32_e32 v73, 0xffff0000, v65
	v_mul_f32_e32 v65, 0xbfb8aa3b, v72
	v_exp_f32_e32 v65, v65
	s_nop 0
	v_add_f32_e32 v65, 1.0, v65
	v_rcp_f32_e32 v74, v65
	v_mul_f32_e32 v65, 0xbfb8aa3b, v73
	v_exp_f32_e32 v65, v65
	s_nop 0
	v_add_f32_e32 v65, 1.0, v65
	v_rcp_f32_e32 v75, v65
	s_nop 0
	v_mul_f32_e64 v72, v74, v72
	v_mul_f32_e64 v73, v75, v73
	s_nop 0
	v_mul_f32_e64 v72, v72, v82
	v_mul_f32_e64 v73, v73, v83
	s_nop 0
	v_cvt_pk_bf16_f32 v65, v72, v73
	v_lshlrev_b32_e32 v72, 16, v70
	v_and_b32_e32 v73, 0xffff0000, v70
	v_mul_f32_e32 v70, 0xbfb8aa3b, v72
	v_exp_f32_e32 v70, v70
	s_nop 0
	v_add_f32_e32 v70, 1.0, v70
	v_rcp_f32_e32 v74, v70
	v_mul_f32_e32 v70, 0xbfb8aa3b, v73
	v_exp_f32_e32 v70, v70
	s_nop 0
	v_add_f32_e32 v70, 1.0, v70
	v_rcp_f32_e32 v75, v70
	s_nop 0
	v_mul_f32_e64 v72, v74, v72
	v_mul_f32_e64 v73, v75, v73
	s_nop 0
	v_mul_f32_e64 v72, v72, v76
	v_mul_f32_e64 v73, v73, v77
	s_nop 0
	v_cvt_pk_bf16_f32 v70, v72, v73
	v_lshlrev_b32_e32 v72, 16, v66
	v_and_b32_e32 v73, 0xffff0000, v66
	v_mul_f32_e32 v66, 0xbfb8aa3b, v72
	v_exp_f32_e32 v66, v66
	s_nop 0
	v_add_f32_e32 v66, 1.0, v66
	v_rcp_f32_e32 v74, v66
	v_mul_f32_e32 v66, 0xbfb8aa3b, v73
	v_exp_f32_e32 v66, v66
	s_nop 0
	v_add_f32_e32 v66, 1.0, v66
	v_rcp_f32_e32 v75, v66
	s_nop 0
	v_mul_f32_e64 v72, v74, v72
	v_mul_f32_e64 v73, v75, v73
	s_waitcnt lgkmcnt(0)
	v_mul_f32_e64 v72, v72, v84
	v_mul_f32_e64 v73, v73, v85
	s_nop 0
	v_cvt_pk_bf16_f32 v66, v72, v73
	v_lshlrev_b32_e32 v72, 16, v71
	v_and_b32_e32 v73, 0xffff0000, v71
	v_mul_f32_e32 v71, 0xbfb8aa3b, v72
	v_exp_f32_e32 v71, v71
	s_nop 0
	v_add_f32_e32 v71, 1.0, v71
	v_rcp_f32_e32 v74, v71
	v_mul_f32_e32 v71, 0xbfb8aa3b, v73
	v_exp_f32_e32 v71, v71
	s_nop 0
	v_add_f32_e32 v71, 1.0, v71
	v_rcp_f32_e32 v75, v71
	s_nop 0
	v_mul_f32_e64 v72, v74, v72
	v_mul_f32_e64 v73, v75, v73
	s_nop 0
	v_mul_f32_e64 v72, v72, v78
	v_mul_f32_e64 v73, v73, v79
	s_nop 0
	v_cvt_pk_bf16_f32 v71, v72, v73
	v_lshlrev_b32_e32 v72, 16, v67
	v_and_b32_e32 v73, 0xffff0000, v67
	v_mul_f32_e32 v67, 0xbfb8aa3b, v72
	v_exp_f32_e32 v67, v67
	s_nop 0
	v_add_f32_e32 v67, 1.0, v67
	v_rcp_f32_e32 v74, v67
	v_mul_f32_e32 v67, 0xbfb8aa3b, v73
	v_exp_f32_e32 v67, v67
	s_nop 0
	v_add_f32_e32 v67, 1.0, v67
	v_rcp_f32_e32 v75, v67
	s_nop 0
	v_mul_f32_e64 v72, v74, v72
	v_mul_f32_e64 v73, v75, v73
	s_nop 0
	v_mul_f32_e64 v72, v72, v86
	v_mul_f32_e64 v73, v73, v87
	s_nop 0
	v_cvt_pk_bf16_f32 v67, v72, v73
	v_mad_i64_i32 v[72:73], s[16:17], v202, s90, v[180:181]
	global_store_dwordx4 v[72:73], v[68:71], off
	s_nop 1
	v_mad_i64_i32 v[68:69], s[16:17], v202, s90, v[182:183]
	v_add_co_u32_e32 v68, vcc, 0x17320000, v68
	s_nop 1
	v_addc_co_u32_e32 v69, vcc, 0, v69, vcc
	global_store_dwordx4 v[68:69], v[64:67], off offset:16
	s_cbranch_scc0 .LBB0_1674
	s_branch .LBB0_1657
